# GEMM K-loops: the s_setprio 0 / s_setprio 1 flip pair in the middle of each 32-MFMA block removed (priority stays raised through the block)
# baseline (speedup 1.0000x reference)
.LBB0_165:
	ds_read_b128 v[144:147], v153
	ds_read_b128 v[158:161], v153 offset:1024
	ds_read_b128 v[162:165], v153 offset:2048
	ds_read_b128 v[166:169], v153 offset:3072
	ds_read_b128 v[170:173], v154
	ds_read_b128 v[174:177], v154 offset:1024
	ds_read_b128 v[180:183], v154 offset:2048
	ds_read_b128 v[184:187], v154 offset:3072
	s_add_u32 s28, s26, 0xfff80080
	s_addc_u32 s29, s27, -1
	s_cmp_eq_u32 s24, 28
	s_cselect_b32 s83, s13, s29
	s_cselect_b32 s82, s20, s28
	s_cselect_b32 s29, s11, s23
	s_cselect_b32 s28, s21, s22
	v_lshl_add_u64 v[148:149], s[26:27], 0, v[136:137]
	s_add_i32 m0, s35, 0xc000
	ds_read_b128 v[192:195], v155
	ds_read_b128 v[196:199], v155 offset:1024
	ds_read_b128 v[200:203], v155 offset:2048
	ds_read_b128 v[204:207], v155 offset:3072
	ds_read_b128 v[208:211], v155 offset:4096
	ds_read_b128 v[212:215], v155 offset:5120
	ds_read_b128 v[216:219], v155 offset:6144
	ds_read_b128 v[220:223], v155 offset:7168
	global_load_lds_dwordx4 v[148:149], off
	v_lshl_add_u64 v[148:149], s[26:27], 0, v[138:139]
	s_add_i32 m0, s35, 0xe000
	s_nop 0
	global_load_lds_dwordx4 v[148:149], off
	s_waitcnt vmcnt(8)
	s_waitcnt lgkmcnt(0)
	s_barrier
	s_setprio 1
	s_waitcnt lgkmcnt(0)
	v_mfma_f32_16x16x32_bf16 v[124:127], v[144:147], v[192:195], v[124:127]
	v_mfma_f32_16x16x32_bf16 v[116:119], v[162:165], v[192:195], v[116:119]
	v_mfma_f32_16x16x32_bf16 v[108:111], v[144:147], v[200:203], v[108:111]
	v_mfma_f32_16x16x32_bf16 v[100:103], v[162:165], v[200:203], v[100:103]
	v_mfma_f32_16x16x32_bf16 v[92:95], v[144:147], v[208:211], v[92:95]
	v_mfma_f32_16x16x32_bf16 v[84:87], v[162:165], v[208:211], v[84:87]
	v_mfma_f32_16x16x32_bf16 v[76:79], v[144:147], v[216:219], v[76:79]
	v_mfma_f32_16x16x32_bf16 v[68:71], v[162:165], v[216:219], v[68:71]
	v_mfma_f32_16x16x32_bf16 v[124:127], v[158:161], v[196:199], v[124:127]
	v_mfma_f32_16x16x32_bf16 v[116:119], v[166:169], v[196:199], v[116:119]
	v_mfma_f32_16x16x32_bf16 v[108:111], v[158:161], v[204:207], v[108:111]
	v_mfma_f32_16x16x32_bf16 v[100:103], v[166:169], v[204:207], v[100:103]
	v_mfma_f32_16x16x32_bf16 v[92:95], v[158:161], v[212:215], v[92:95]
	v_mfma_f32_16x16x32_bf16 v[84:87], v[166:169], v[212:215], v[84:87]
	v_mfma_f32_16x16x32_bf16 v[76:79], v[158:161], v[220:223], v[76:79]
	v_mfma_f32_16x16x32_bf16 v[68:71], v[166:169], v[220:223], v[68:71]
	v_mfma_f32_16x16x32_bf16 v[120:123], v[170:173], v[192:195], v[120:123]
	v_mfma_f32_16x16x32_bf16 v[112:115], v[180:183], v[192:195], v[112:115]
	v_mfma_f32_16x16x32_bf16 v[104:107], v[170:173], v[200:203], v[104:107]
	v_mfma_f32_16x16x32_bf16 v[96:99], v[180:183], v[200:203], v[96:99]
	v_mfma_f32_16x16x32_bf16 v[88:91], v[170:173], v[208:211], v[88:91]
	v_mfma_f32_16x16x32_bf16 v[80:83], v[180:183], v[208:211], v[80:83]
	v_mfma_f32_16x16x32_bf16 v[72:75], v[170:173], v[216:219], v[72:75]
	v_mfma_f32_16x16x32_bf16 v[64:67], v[180:183], v[216:219], v[64:67]
	v_mfma_f32_16x16x32_bf16 v[120:123], v[174:177], v[196:199], v[120:123]
	v_mfma_f32_16x16x32_bf16 v[112:115], v[184:187], v[196:199], v[112:115]
	v_mfma_f32_16x16x32_bf16 v[104:107], v[174:177], v[204:207], v[104:107]
	v_mfma_f32_16x16x32_bf16 v[96:99], v[184:187], v[204:207], v[96:99]
	v_mfma_f32_16x16x32_bf16 v[88:91], v[174:177], v[212:215], v[88:91]
	v_mfma_f32_16x16x32_bf16 v[80:83], v[184:187], v[212:215], v[80:83]
	v_mfma_f32_16x16x32_bf16 v[72:75], v[174:177], v[220:223], v[72:75]
	v_mfma_f32_16x16x32_bf16 v[64:67], v[184:187], v[220:223], v[64:67]
	s_setprio 0
	s_barrier
	s_add_i32 s46, s44, s25
	v_lshl_add_u64 v[148:149], s[28:29], 0, v[132:133]
	s_mov_b32 m0, s46
	ds_read_b128 v[192:195], v155 offset:16384
	ds_read_b128 v[196:199], v155 offset:17408
	ds_read_b128 v[200:203], v155 offset:18432
	ds_read_b128 v[204:207], v155 offset:19456
	ds_read_b128 v[208:211], v155 offset:20480
	ds_read_b128 v[212:215], v155 offset:21504
	ds_read_b128 v[216:219], v155 offset:22528
	ds_read_b128 v[220:223], v155 offset:23552
	global_load_lds_dwordx4 v[148:149], off
	s_add_i32 m0, s46, 0x2000
	s_add_u32 s70, s28, 0x80000
	v_lshl_add_u64 v[188:189], s[28:29], 0, v[128:129]
	s_addc_u32 s71, s29, 0
	s_add_i32 s46, s45, s25
	global_load_lds_dwordx4 v[188:189], off
	v_lshl_add_u64 v[224:225], s[70:71], 0, v[132:133]
	s_mov_b32 m0, s46
	v_lshl_add_u64 v[226:227], s[82:83], 0, v[130:131]
	global_load_lds_dwordx4 v[224:225], off
	v_lshl_add_u64 v[224:225], s[70:71], 0, v[128:129]
	s_add_i32 m0, s46, 0x2000
	s_nop 0
	global_load_lds_dwordx4 v[224:225], off
	v_lshl_add_u64 v[224:225], s[82:83], 0, v[134:135]
	s_mov_b32 m0, s35
	s_nop 0
	global_load_lds_dwordx4 v[224:225], off
	s_mov_b32 m0, s36
	s_nop 0
	global_load_lds_dwordx4 v[226:227], off
	s_waitcnt vmcnt(8)
	s_waitcnt lgkmcnt(0)
	s_barrier
	s_setprio 1
	s_waitcnt lgkmcnt(0)
	v_mfma_f32_16x16x32_bf16 v[60:63], v[144:147], v[192:195], v[60:63]
	v_mfma_f32_16x16x32_bf16 v[52:55], v[162:165], v[192:195], v[52:55]
	v_mfma_f32_16x16x32_bf16 v[44:47], v[144:147], v[200:203], v[44:47]
	v_mfma_f32_16x16x32_bf16 v[36:39], v[162:165], v[200:203], v[36:39]
	v_mfma_f32_16x16x32_bf16 v[28:31], v[144:147], v[208:211], v[28:31]
	v_mfma_f32_16x16x32_bf16 v[20:23], v[162:165], v[208:211], v[20:23]
	v_mfma_f32_16x16x32_bf16 v[12:15], v[144:147], v[216:219], v[12:15]
	v_mfma_f32_16x16x32_bf16 v[4:7], v[162:165], v[216:219], v[4:7]
	v_mfma_f32_16x16x32_bf16 v[60:63], v[158:161], v[196:199], v[60:63]
	v_mfma_f32_16x16x32_bf16 v[52:55], v[166:169], v[196:199], v[52:55]
	v_mfma_f32_16x16x32_bf16 v[44:47], v[158:161], v[204:207], v[44:47]
	v_mfma_f32_16x16x32_bf16 v[36:39], v[166:169], v[204:207], v[36:39]
	v_mfma_f32_16x16x32_bf16 v[28:31], v[158:161], v[212:215], v[28:31]
	v_mfma_f32_16x16x32_bf16 v[20:23], v[166:169], v[212:215], v[20:23]
	v_mfma_f32_16x16x32_bf16 v[12:15], v[158:161], v[220:223], v[12:15]
	v_mfma_f32_16x16x32_bf16 v[4:7], v[166:169], v[220:223], v[4:7]
	v_mfma_f32_16x16x32_bf16 v[56:59], v[170:173], v[192:195], v[56:59]
	v_mfma_f32_16x16x32_bf16 v[48:51], v[180:183], v[192:195], v[48:51]
	v_mfma_f32_16x16x32_bf16 v[40:43], v[170:173], v[200:203], v[40:43]
	v_mfma_f32_16x16x32_bf16 v[32:35], v[180:183], v[200:203], v[32:35]
	v_mfma_f32_16x16x32_bf16 v[24:27], v[170:173], v[208:211], v[24:27]
	v_mfma_f32_16x16x32_bf16 v[16:19], v[180:183], v[208:211], v[16:19]
	v_mfma_f32_16x16x32_bf16 v[8:11], v[170:173], v[216:219], v[8:11]
	v_mfma_f32_16x16x32_bf16 v[0:3], v[180:183], v[216:219], v[0:3]
	v_mfma_f32_16x16x32_bf16 v[56:59], v[174:177], v[196:199], v[56:59]
	v_mfma_f32_16x16x32_bf16 v[48:51], v[184:187], v[196:199], v[48:51]
	v_mfma_f32_16x16x32_bf16 v[40:43], v[174:177], v[204:207], v[40:43]
	v_mfma_f32_16x16x32_bf16 v[32:35], v[184:187], v[204:207], v[32:35]
	v_mfma_f32_16x16x32_bf16 v[24:27], v[174:177], v[212:215], v[24:27]
	v_mfma_f32_16x16x32_bf16 v[16:19], v[184:187], v[212:215], v[16:19]
	v_mfma_f32_16x16x32_bf16 v[8:11], v[174:177], v[220:223], v[8:11]
	v_mfma_f32_16x16x32_bf16 v[0:3], v[184:187], v[220:223], v[0:3]
	s_setprio 0
	s_barrier
	s_add_i32 s46, 0, 0x18000
	v_add_u32_e32 v157, s46, v151
	s_add_i32 s72, 0, 0x1c000
	ds_read_b128 v[144:147], v157
	ds_read_b128 v[158:161], v157 offset:1024
	ds_read_b128 v[162:165], v157 offset:2048
	ds_read_b128 v[166:169], v157 offset:3072
	v_add_u32_e32 v157, s72, v151
	ds_read_b128 v[170:173], v157
	ds_read_b128 v[174:177], v157 offset:1024
	ds_read_b128 v[180:183], v157 offset:2048
	ds_read_b128 v[184:187], v157 offset:3072
	s_add_u32 s70, s82, 0x80000
	s_addc_u32 s71, s83, 0
	s_mov_b32 m0, s37
	v_lshl_add_u64 v[228:229], s[70:71], 0, v[134:135]
	ds_read_b128 v[192:195], v155 offset:32768
	ds_read_b128 v[196:199], v155 offset:33792
	ds_read_b128 v[200:203], v155 offset:34816
	ds_read_b128 v[204:207], v155 offset:35840
	ds_read_b128 v[208:211], v155 offset:36864
	ds_read_b128 v[212:215], v155 offset:37888
	ds_read_b128 v[216:219], v155 offset:38912
	ds_read_b128 v[220:223], v155 offset:39936
	global_load_lds_dwordx4 v[228:229], off
	v_lshl_add_u64 v[228:229], s[70:71], 0, v[130:131]
	s_mov_b32 m0, s38
	s_nop 0
	global_load_lds_dwordx4 v[228:229], off
	s_waitcnt vmcnt(8)
	s_waitcnt lgkmcnt(0)
	s_barrier
	s_setprio 1
	s_waitcnt lgkmcnt(0)
	v_mfma_f32_16x16x32_bf16 v[124:127], v[144:147], v[192:195], v[124:127]
	v_mfma_f32_16x16x32_bf16 v[116:119], v[162:165], v[192:195], v[116:119]
	v_mfma_f32_16x16x32_bf16 v[108:111], v[144:147], v[200:203], v[108:111]
	v_mfma_f32_16x16x32_bf16 v[100:103], v[162:165], v[200:203], v[100:103]
	v_mfma_f32_16x16x32_bf16 v[92:95], v[144:147], v[208:211], v[92:95]
	v_mfma_f32_16x16x32_bf16 v[84:87], v[162:165], v[208:211], v[84:87]
	v_mfma_f32_16x16x32_bf16 v[76:79], v[144:147], v[216:219], v[76:79]
	v_mfma_f32_16x16x32_bf16 v[68:71], v[162:165], v[216:219], v[68:71]
	v_mfma_f32_16x16x32_bf16 v[124:127], v[158:161], v[196:199], v[124:127]
	v_mfma_f32_16x16x32_bf16 v[116:119], v[166:169], v[196:199], v[116:119]
	v_mfma_f32_16x16x32_bf16 v[108:111], v[158:161], v[204:207], v[108:111]
	v_mfma_f32_16x16x32_bf16 v[100:103], v[166:169], v[204:207], v[100:103]
	v_mfma_f32_16x16x32_bf16 v[92:95], v[158:161], v[212:215], v[92:95]
	v_mfma_f32_16x16x32_bf16 v[84:87], v[166:169], v[212:215], v[84:87]
	v_mfma_f32_16x16x32_bf16 v[76:79], v[158:161], v[220:223], v[76:79]
	v_mfma_f32_16x16x32_bf16 v[68:71], v[166:169], v[220:223], v[68:71]
	v_mfma_f32_16x16x32_bf16 v[120:123], v[170:173], v[192:195], v[120:123]
	v_mfma_f32_16x16x32_bf16 v[112:115], v[180:183], v[192:195], v[112:115]
	v_mfma_f32_16x16x32_bf16 v[104:107], v[170:173], v[200:203], v[104:107]
	v_mfma_f32_16x16x32_bf16 v[96:99], v[180:183], v[200:203], v[96:99]
	v_mfma_f32_16x16x32_bf16 v[88:91], v[170:173], v[208:211], v[88:91]
	v_mfma_f32_16x16x32_bf16 v[80:83], v[180:183], v[208:211], v[80:83]
	v_mfma_f32_16x16x32_bf16 v[72:75], v[170:173], v[216:219], v[72:75]
	v_mfma_f32_16x16x32_bf16 v[64:67], v[180:183], v[216:219], v[64:67]
	v_mfma_f32_16x16x32_bf16 v[120:123], v[174:177], v[196:199], v[120:123]
	v_mfma_f32_16x16x32_bf16 v[112:115], v[184:187], v[196:199], v[112:115]
	v_mfma_f32_16x16x32_bf16 v[104:107], v[174:177], v[204:207], v[104:107]
	v_mfma_f32_16x16x32_bf16 v[96:99], v[184:187], v[204:207], v[96:99]
	v_mfma_f32_16x16x32_bf16 v[88:91], v[174:177], v[212:215], v[88:91]
	v_mfma_f32_16x16x32_bf16 v[80:83], v[184:187], v[212:215], v[80:83]
	v_mfma_f32_16x16x32_bf16 v[72:75], v[174:177], v[220:223], v[72:75]
	v_mfma_f32_16x16x32_bf16 v[64:67], v[184:187], v[220:223], v[64:67]
	s_setprio 0
	s_barrier
	s_add_i32 s46, s46, s25
	v_lshl_add_u64 v[148:149], v[148:149], 0, s[6:7]
	s_mov_b32 m0, s46
	ds_read_b128 v[192:195], v155 offset:49152
	ds_read_b128 v[196:199], v155 offset:50176
	ds_read_b128 v[200:203], v155 offset:51200
	ds_read_b128 v[204:207], v155 offset:52224
	ds_read_b128 v[208:211], v155 offset:53248
	ds_read_b128 v[212:215], v155 offset:54272
	ds_read_b128 v[216:219], v155 offset:55296
	ds_read_b128 v[220:223], v155 offset:56320
	global_load_lds_dwordx4 v[148:149], off
	s_add_i32 m0, s46, 0x2000
	s_add_u32 s28, s28, 0x80080
	v_lshl_add_u64 v[148:149], v[188:189], 0, s[6:7]
	s_addc_u32 s29, s29, 0
	s_add_i32 s46, s72, s25
	global_load_lds_dwordx4 v[148:149], off
	v_lshl_add_u64 v[148:149], s[28:29], 0, v[132:133]
	s_mov_b32 m0, s46
	s_nop 0
	global_load_lds_dwordx4 v[148:149], off
	v_lshl_add_u64 v[148:149], s[28:29], 0, v[128:129]
	s_add_i32 m0, s46, 0x2000
	s_nop 0
	global_load_lds_dwordx4 v[148:149], off
	v_lshl_add_u64 v[148:149], v[224:225], 0, s[6:7]
	s_mov_b32 m0, s42
	s_nop 0
	global_load_lds_dwordx4 v[148:149], off
	v_lshl_add_u64 v[148:149], v[226:227], 0, s[6:7]
	s_mov_b32 m0, s43
	s_nop 0
	global_load_lds_dwordx4 v[148:149], off
	s_waitcnt vmcnt(8)
	s_waitcnt lgkmcnt(0)
	s_barrier
	s_setprio 1
	s_waitcnt lgkmcnt(0)
	v_mfma_f32_16x16x32_bf16 v[60:63], v[144:147], v[192:195], v[60:63]
	v_mfma_f32_16x16x32_bf16 v[52:55], v[162:165], v[192:195], v[52:55]
	v_mfma_f32_16x16x32_bf16 v[44:47], v[144:147], v[200:203], v[44:47]
	v_mfma_f32_16x16x32_bf16 v[36:39], v[162:165], v[200:203], v[36:39]
	v_mfma_f32_16x16x32_bf16 v[28:31], v[144:147], v[208:211], v[28:31]
	v_mfma_f32_16x16x32_bf16 v[20:23], v[162:165], v[208:211], v[20:23]
	v_mfma_f32_16x16x32_bf16 v[12:15], v[144:147], v[216:219], v[12:15]
	v_mfma_f32_16x16x32_bf16 v[4:7], v[162:165], v[216:219], v[4:7]
	v_mfma_f32_16x16x32_bf16 v[60:63], v[158:161], v[196:199], v[60:63]
	v_mfma_f32_16x16x32_bf16 v[52:55], v[166:169], v[196:199], v[52:55]
	v_mfma_f32_16x16x32_bf16 v[44:47], v[158:161], v[204:207], v[44:47]
	v_mfma_f32_16x16x32_bf16 v[36:39], v[166:169], v[204:207], v[36:39]
	v_mfma_f32_16x16x32_bf16 v[28:31], v[158:161], v[212:215], v[28:31]
	v_mfma_f32_16x16x32_bf16 v[20:23], v[166:169], v[212:215], v[20:23]
	v_mfma_f32_16x16x32_bf16 v[12:15], v[158:161], v[220:223], v[12:15]
	v_mfma_f32_16x16x32_bf16 v[4:7], v[166:169], v[220:223], v[4:7]
	v_mfma_f32_16x16x32_bf16 v[56:59], v[170:173], v[192:195], v[56:59]
	v_mfma_f32_16x16x32_bf16 v[48:51], v[180:183], v[192:195], v[48:51]
	v_mfma_f32_16x16x32_bf16 v[40:43], v[170:173], v[200:203], v[40:43]
	v_mfma_f32_16x16x32_bf16 v[32:35], v[180:183], v[200:203], v[32:35]
	v_mfma_f32_16x16x32_bf16 v[24:27], v[170:173], v[208:211], v[24:27]
	v_mfma_f32_16x16x32_bf16 v[16:19], v[180:183], v[208:211], v[16:19]
	v_mfma_f32_16x16x32_bf16 v[8:11], v[170:173], v[216:219], v[8:11]
	v_mfma_f32_16x16x32_bf16 v[0:3], v[180:183], v[216:219], v[0:3]
	v_mfma_f32_16x16x32_bf16 v[56:59], v[174:177], v[196:199], v[56:59]
	v_mfma_f32_16x16x32_bf16 v[48:51], v[184:187], v[196:199], v[48:51]
	v_mfma_f32_16x16x32_bf16 v[40:43], v[174:177], v[204:207], v[40:43]
	v_mfma_f32_16x16x32_bf16 v[32:35], v[184:187], v[204:207], v[32:35]
	v_mfma_f32_16x16x32_bf16 v[24:27], v[174:177], v[212:215], v[24:27]
	v_mfma_f32_16x16x32_bf16 v[16:19], v[184:187], v[212:215], v[16:19]
	v_mfma_f32_16x16x32_bf16 v[8:11], v[174:177], v[220:223], v[8:11]
	v_mfma_f32_16x16x32_bf16 v[0:3], v[184:187], v[220:223], v[0:3]
	s_setprio 0
	s_barrier
	s_add_i32 s24, s24, 2
	s_add_u32 s26, s26, 0x100
	s_addc_u32 s27, s27, 0
	s_add_u32 s22, s22, 0x100
	s_addc_u32 s23, s23, 0
	s_cmp_gt_u32 s24, 29
	s_cbranch_scc0 .LBB0_165
	s_and_b64 vcc, exec, s[8:9]
	s_cbranch_vccz .LBB0_168
	s_barrier

.LBB0_263:
	ds_read_b128 v[140:143], v147
	ds_read_b128 v[150:153], v147 offset:1024
	ds_read_b128 v[154:157], v147 offset:2048
	ds_read_b128 v[158:161], v147 offset:3072
	ds_read_b128 v[162:165], v148
	ds_read_b128 v[166:169], v148 offset:1024
	ds_read_b128 v[170:173], v148 offset:2048
	ds_read_b128 v[174:177], v148 offset:3072
	s_add_u32 s28, s26, 0x100
	s_addc_u32 s29, s27, 0
	s_cmpk_eq_i32 s46, 0x54
	s_cselect_b32 s85, s9, s29
	s_cselect_b32 s84, s8, s28
	s_cselect_b32 s83, s15, s45
	s_cselect_b32 s82, s14, s44
	v_lshl_add_u64 v[188:189], s[26:27], 0, v[132:133]
	s_add_i32 m0, s21, 0xc000
	ds_read_b128 v[180:183], v149
	ds_read_b128 v[184:187], v149 offset:1024
	ds_read_b128 v[192:195], v149 offset:2048
	ds_read_b128 v[196:199], v149 offset:3072
	ds_read_b128 v[200:203], v149 offset:4096
	ds_read_b128 v[204:207], v149 offset:5120
	ds_read_b128 v[208:211], v149 offset:6144
	ds_read_b128 v[212:215], v149 offset:7168
	global_load_lds_dwordx4 v[188:189], off
	v_lshl_add_u64 v[188:189], s[26:27], 0, v[134:135]
	s_add_i32 m0, s21, 0xe000
	s_nop 0
	global_load_lds_dwordx4 v[188:189], off
	s_waitcnt vmcnt(8)
	s_waitcnt lgkmcnt(0)
	s_barrier
	s_setprio 1
	s_waitcnt lgkmcnt(0)
	v_mfma_f32_16x16x32_bf16 v[124:127], v[140:143], v[180:183], v[124:127]
	v_mfma_f32_16x16x32_bf16 v[120:123], v[154:157], v[180:183], v[120:123]
	v_mfma_f32_16x16x32_bf16 v[108:111], v[140:143], v[192:195], v[108:111]
	v_mfma_f32_16x16x32_bf16 v[104:107], v[154:157], v[192:195], v[104:107]
	v_mfma_f32_16x16x32_bf16 v[92:95], v[140:143], v[200:203], v[92:95]
	v_mfma_f32_16x16x32_bf16 v[88:91], v[154:157], v[200:203], v[88:91]
	v_mfma_f32_16x16x32_bf16 v[76:79], v[140:143], v[208:211], v[76:79]
	v_mfma_f32_16x16x32_bf16 v[72:75], v[154:157], v[208:211], v[72:75]
	v_mfma_f32_16x16x32_bf16 v[124:127], v[150:153], v[184:187], v[124:127]
	v_mfma_f32_16x16x32_bf16 v[120:123], v[158:161], v[184:187], v[120:123]
	v_mfma_f32_16x16x32_bf16 v[108:111], v[150:153], v[196:199], v[108:111]
	v_mfma_f32_16x16x32_bf16 v[104:107], v[158:161], v[196:199], v[104:107]
	v_mfma_f32_16x16x32_bf16 v[92:95], v[150:153], v[204:207], v[92:95]
	v_mfma_f32_16x16x32_bf16 v[88:91], v[158:161], v[204:207], v[88:91]
	v_mfma_f32_16x16x32_bf16 v[76:79], v[150:153], v[212:215], v[76:79]
	v_mfma_f32_16x16x32_bf16 v[72:75], v[158:161], v[212:215], v[72:75]
	v_mfma_f32_16x16x32_bf16 v[116:119], v[162:165], v[180:183], v[116:119]
	v_mfma_f32_16x16x32_bf16 v[112:115], v[170:173], v[180:183], v[112:115]
	v_mfma_f32_16x16x32_bf16 v[100:103], v[162:165], v[192:195], v[100:103]
	v_mfma_f32_16x16x32_bf16 v[96:99], v[170:173], v[192:195], v[96:99]
	v_mfma_f32_16x16x32_bf16 v[84:87], v[162:165], v[200:203], v[84:87]
	v_mfma_f32_16x16x32_bf16 v[80:83], v[170:173], v[200:203], v[80:83]
	v_mfma_f32_16x16x32_bf16 v[68:71], v[162:165], v[208:211], v[68:71]
	v_mfma_f32_16x16x32_bf16 v[64:67], v[170:173], v[208:211], v[64:67]
	v_mfma_f32_16x16x32_bf16 v[116:119], v[166:169], v[184:187], v[116:119]
	v_mfma_f32_16x16x32_bf16 v[112:115], v[174:177], v[184:187], v[112:115]
	v_mfma_f32_16x16x32_bf16 v[100:103], v[166:169], v[196:199], v[100:103]
	v_mfma_f32_16x16x32_bf16 v[96:99], v[174:177], v[196:199], v[96:99]
	v_mfma_f32_16x16x32_bf16 v[84:87], v[166:169], v[204:207], v[84:87]
	v_mfma_f32_16x16x32_bf16 v[80:83], v[174:177], v[204:207], v[80:83]
	v_mfma_f32_16x16x32_bf16 v[68:71], v[166:169], v[212:215], v[68:71]
	v_mfma_f32_16x16x32_bf16 v[64:67], v[174:177], v[212:215], v[64:67]
	s_setprio 0
	s_barrier
	s_add_i32 s26, s36, s20
	v_lshl_add_u64 v[188:189], s[82:83], 0, v[128:129]
	s_mov_b32 m0, s26
	ds_read_b128 v[180:183], v149 offset:16384
	ds_read_b128 v[184:187], v149 offset:17408
	ds_read_b128 v[192:195], v149 offset:18432
	ds_read_b128 v[196:199], v149 offset:19456
	ds_read_b128 v[200:203], v149 offset:20480
	ds_read_b128 v[204:207], v149 offset:21504
	ds_read_b128 v[208:211], v149 offset:22528
	ds_read_b128 v[212:215], v149 offset:23552
	global_load_lds_dwordx4 v[188:189], off
	s_add_i32 m0, s26, 0x2000
	s_add_u32 s26, s82, 0x160000
	v_lshl_add_u64 v[216:217], s[82:83], 0, v[130:131]
	s_addc_u32 s27, s83, 0
	s_add_i32 s47, s37, s20
	global_load_lds_dwordx4 v[216:217], off
	v_lshl_add_u64 v[218:219], s[26:27], 0, v[128:129]
	s_mov_b32 m0, s47
	v_lshl_add_u64 v[220:221], s[84:85], 0, v[130:131]
	global_load_lds_dwordx4 v[218:219], off
	v_lshl_add_u64 v[218:219], s[26:27], 0, v[130:131]
	s_add_i32 m0, s47, 0x2000
	s_nop 0
	global_load_lds_dwordx4 v[218:219], off
	v_lshl_add_u64 v[218:219], s[84:85], 0, v[128:129]
	s_mov_b32 m0, s21
	s_nop 0
	global_load_lds_dwordx4 v[218:219], off
	s_mov_b32 m0, s22
	s_nop 0
	global_load_lds_dwordx4 v[220:221], off
	s_waitcnt vmcnt(8)
	s_waitcnt lgkmcnt(0)
	s_barrier
	s_setprio 1
	s_waitcnt lgkmcnt(0)
	v_mfma_f32_16x16x32_bf16 v[60:63], v[140:143], v[180:183], v[60:63]
	v_mfma_f32_16x16x32_bf16 v[56:59], v[154:157], v[180:183], v[56:59]
	v_mfma_f32_16x16x32_bf16 v[44:47], v[140:143], v[192:195], v[44:47]
	v_mfma_f32_16x16x32_bf16 v[40:43], v[154:157], v[192:195], v[40:43]
	v_mfma_f32_16x16x32_bf16 v[28:31], v[140:143], v[200:203], v[28:31]
	v_mfma_f32_16x16x32_bf16 v[24:27], v[154:157], v[200:203], v[24:27]
	v_mfma_f32_16x16x32_bf16 v[12:15], v[140:143], v[208:211], v[12:15]
	v_mfma_f32_16x16x32_bf16 v[8:11], v[154:157], v[208:211], v[8:11]
	v_mfma_f32_16x16x32_bf16 v[60:63], v[150:153], v[184:187], v[60:63]
	v_mfma_f32_16x16x32_bf16 v[56:59], v[158:161], v[184:187], v[56:59]
	v_mfma_f32_16x16x32_bf16 v[44:47], v[150:153], v[196:199], v[44:47]
	v_mfma_f32_16x16x32_bf16 v[40:43], v[158:161], v[196:199], v[40:43]
	v_mfma_f32_16x16x32_bf16 v[28:31], v[150:153], v[204:207], v[28:31]
	v_mfma_f32_16x16x32_bf16 v[24:27], v[158:161], v[204:207], v[24:27]
	v_mfma_f32_16x16x32_bf16 v[12:15], v[150:153], v[212:215], v[12:15]
	v_mfma_f32_16x16x32_bf16 v[8:11], v[158:161], v[212:215], v[8:11]
	v_mfma_f32_16x16x32_bf16 v[52:55], v[162:165], v[180:183], v[52:55]
	v_mfma_f32_16x16x32_bf16 v[48:51], v[170:173], v[180:183], v[48:51]
	v_mfma_f32_16x16x32_bf16 v[36:39], v[162:165], v[192:195], v[36:39]
	v_mfma_f32_16x16x32_bf16 v[32:35], v[170:173], v[192:195], v[32:35]
	v_mfma_f32_16x16x32_bf16 v[20:23], v[162:165], v[200:203], v[20:23]
	v_mfma_f32_16x16x32_bf16 v[16:19], v[170:173], v[200:203], v[16:19]
	v_mfma_f32_16x16x32_bf16 v[4:7], v[162:165], v[208:211], v[4:7]
	v_mfma_f32_16x16x32_bf16 v[0:3], v[170:173], v[208:211], v[0:3]
	v_mfma_f32_16x16x32_bf16 v[52:55], v[166:169], v[184:187], v[52:55]
	v_mfma_f32_16x16x32_bf16 v[48:51], v[174:177], v[184:187], v[48:51]
	v_mfma_f32_16x16x32_bf16 v[36:39], v[166:169], v[196:199], v[36:39]
	v_mfma_f32_16x16x32_bf16 v[32:35], v[174:177], v[196:199], v[32:35]
	v_mfma_f32_16x16x32_bf16 v[20:23], v[166:169], v[204:207], v[20:23]
	v_mfma_f32_16x16x32_bf16 v[16:19], v[174:177], v[204:207], v[16:19]
	v_mfma_f32_16x16x32_bf16 v[4:7], v[166:169], v[212:215], v[4:7]
	v_mfma_f32_16x16x32_bf16 v[0:3], v[174:177], v[212:215], v[0:3]
	s_setprio 0
	s_barrier
	s_add_i32 s47, 0, 0x18000
	s_add_i32 s70, 0, 0x1c000
	v_add_u32_e32 v158, s47, v145
	v_add_u32_e32 v174, s70, v145
	ds_read_b128 v[140:143], v158
	ds_read_b128 v[150:153], v158 offset:1024
	ds_read_b128 v[154:157], v158 offset:2048
	ds_read_b128 v[158:161], v158 offset:3072
	ds_read_b128 v[162:165], v174
	ds_read_b128 v[166:169], v174 offset:1024
	ds_read_b128 v[170:173], v174 offset:2048
	ds_read_b128 v[174:177], v174 offset:3072
	s_add_u32 s26, s84, 0x160000
	s_addc_u32 s27, s85, 0
	s_mov_b32 m0, s23
	v_lshl_add_u64 v[222:223], s[26:27], 0, v[128:129]
	ds_read_b128 v[180:183], v149 offset:32768
	ds_read_b128 v[184:187], v149 offset:33792
	ds_read_b128 v[192:195], v149 offset:34816
	ds_read_b128 v[196:199], v149 offset:35840
	ds_read_b128 v[200:203], v149 offset:36864
	ds_read_b128 v[204:207], v149 offset:37888
	ds_read_b128 v[208:211], v149 offset:38912
	ds_read_b128 v[212:215], v149 offset:39936
	global_load_lds_dwordx4 v[222:223], off
	v_lshl_add_u64 v[222:223], s[26:27], 0, v[130:131]
	s_mov_b32 m0, s24
	s_nop 0
	global_load_lds_dwordx4 v[222:223], off
	s_waitcnt vmcnt(8)
	s_waitcnt lgkmcnt(0)
	s_barrier
	s_setprio 1
	s_waitcnt lgkmcnt(0)
	v_mfma_f32_16x16x32_bf16 v[124:127], v[140:143], v[180:183], v[124:127]
	v_mfma_f32_16x16x32_bf16 v[120:123], v[154:157], v[180:183], v[120:123]
	v_mfma_f32_16x16x32_bf16 v[108:111], v[140:143], v[192:195], v[108:111]
	v_mfma_f32_16x16x32_bf16 v[104:107], v[154:157], v[192:195], v[104:107]
	v_mfma_f32_16x16x32_bf16 v[92:95], v[140:143], v[200:203], v[92:95]
	v_mfma_f32_16x16x32_bf16 v[88:91], v[154:157], v[200:203], v[88:91]
	v_mfma_f32_16x16x32_bf16 v[76:79], v[140:143], v[208:211], v[76:79]
	v_mfma_f32_16x16x32_bf16 v[72:75], v[154:157], v[208:211], v[72:75]
	v_mfma_f32_16x16x32_bf16 v[124:127], v[150:153], v[184:187], v[124:127]
	v_mfma_f32_16x16x32_bf16 v[120:123], v[158:161], v[184:187], v[120:123]
	v_mfma_f32_16x16x32_bf16 v[108:111], v[150:153], v[196:199], v[108:111]
	v_mfma_f32_16x16x32_bf16 v[104:107], v[158:161], v[196:199], v[104:107]
	v_mfma_f32_16x16x32_bf16 v[92:95], v[150:153], v[204:207], v[92:95]
	v_mfma_f32_16x16x32_bf16 v[88:91], v[158:161], v[204:207], v[88:91]
	v_mfma_f32_16x16x32_bf16 v[76:79], v[150:153], v[212:215], v[76:79]
	v_mfma_f32_16x16x32_bf16 v[72:75], v[158:161], v[212:215], v[72:75]
	v_mfma_f32_16x16x32_bf16 v[116:119], v[162:165], v[180:183], v[116:119]
	v_mfma_f32_16x16x32_bf16 v[112:115], v[170:173], v[180:183], v[112:115]
	v_mfma_f32_16x16x32_bf16 v[100:103], v[162:165], v[192:195], v[100:103]
	v_mfma_f32_16x16x32_bf16 v[96:99], v[170:173], v[192:195], v[96:99]
	v_mfma_f32_16x16x32_bf16 v[84:87], v[162:165], v[200:203], v[84:87]
	v_mfma_f32_16x16x32_bf16 v[80:83], v[170:173], v[200:203], v[80:83]
	v_mfma_f32_16x16x32_bf16 v[68:71], v[162:165], v[208:211], v[68:71]
	v_mfma_f32_16x16x32_bf16 v[64:67], v[170:173], v[208:211], v[64:67]
	v_mfma_f32_16x16x32_bf16 v[116:119], v[166:169], v[184:187], v[116:119]
	v_mfma_f32_16x16x32_bf16 v[112:115], v[174:177], v[184:187], v[112:115]
	v_mfma_f32_16x16x32_bf16 v[100:103], v[166:169], v[196:199], v[100:103]
	v_mfma_f32_16x16x32_bf16 v[96:99], v[174:177], v[196:199], v[96:99]
	v_mfma_f32_16x16x32_bf16 v[84:87], v[166:169], v[204:207], v[84:87]
	v_mfma_f32_16x16x32_bf16 v[80:83], v[174:177], v[204:207], v[80:83]
	v_mfma_f32_16x16x32_bf16 v[68:71], v[166:169], v[212:215], v[68:71]
	v_mfma_f32_16x16x32_bf16 v[64:67], v[174:177], v[212:215], v[64:67]
	s_setprio 0
	s_barrier
	s_add_i32 s26, s47, s20
	v_lshl_add_u64 v[188:189], v[188:189], 0, s[10:11]
	s_mov_b32 m0, s26
	ds_read_b128 v[180:183], v149 offset:49152
	ds_read_b128 v[184:187], v149 offset:50176
	ds_read_b128 v[192:195], v149 offset:51200
	ds_read_b128 v[196:199], v149 offset:52224
	ds_read_b128 v[200:203], v149 offset:53248
	ds_read_b128 v[204:207], v149 offset:54272
	ds_read_b128 v[208:211], v149 offset:55296
	ds_read_b128 v[212:215], v149 offset:56320
	global_load_lds_dwordx4 v[188:189], off
	s_add_i32 m0, s26, 0x2000
	s_add_u32 s26, s82, 0x160080
	v_lshl_add_u64 v[188:189], v[216:217], 0, s[10:11]
	s_addc_u32 s27, s83, 0
	s_add_i32 s47, s70, s20
	global_load_lds_dwordx4 v[188:189], off
	v_lshl_add_u64 v[188:189], s[26:27], 0, v[128:129]
	s_mov_b32 m0, s47
	s_nop 0
	global_load_lds_dwordx4 v[188:189], off
	v_lshl_add_u64 v[188:189], s[26:27], 0, v[130:131]
	s_add_i32 m0, s47, 0x2000
	s_nop 0
	global_load_lds_dwordx4 v[188:189], off
	v_lshl_add_u64 v[188:189], v[218:219], 0, s[10:11]
	s_mov_b32 m0, s33
	s_nop 0
	global_load_lds_dwordx4 v[188:189], off
	v_lshl_add_u64 v[188:189], v[220:221], 0, s[10:11]
	s_mov_b32 m0, s35
	s_nop 0
	global_load_lds_dwordx4 v[188:189], off
	s_waitcnt vmcnt(8)
	s_waitcnt lgkmcnt(0)
	s_barrier
	s_setprio 1
	s_waitcnt lgkmcnt(0)
	v_mfma_f32_16x16x32_bf16 v[60:63], v[140:143], v[180:183], v[60:63]
	v_mfma_f32_16x16x32_bf16 v[56:59], v[154:157], v[180:183], v[56:59]
	v_mfma_f32_16x16x32_bf16 v[44:47], v[140:143], v[192:195], v[44:47]
	v_mfma_f32_16x16x32_bf16 v[40:43], v[154:157], v[192:195], v[40:43]
	v_mfma_f32_16x16x32_bf16 v[28:31], v[140:143], v[200:203], v[28:31]
	v_mfma_f32_16x16x32_bf16 v[24:27], v[154:157], v[200:203], v[24:27]
	v_mfma_f32_16x16x32_bf16 v[12:15], v[140:143], v[208:211], v[12:15]
	v_mfma_f32_16x16x32_bf16 v[8:11], v[154:157], v[208:211], v[8:11]
	v_mfma_f32_16x16x32_bf16 v[60:63], v[150:153], v[184:187], v[60:63]
	v_mfma_f32_16x16x32_bf16 v[56:59], v[158:161], v[184:187], v[56:59]
	v_mfma_f32_16x16x32_bf16 v[44:47], v[150:153], v[196:199], v[44:47]
	v_mfma_f32_16x16x32_bf16 v[40:43], v[158:161], v[196:199], v[40:43]
	v_mfma_f32_16x16x32_bf16 v[28:31], v[150:153], v[204:207], v[28:31]
	v_mfma_f32_16x16x32_bf16 v[24:27], v[158:161], v[204:207], v[24:27]
	v_mfma_f32_16x16x32_bf16 v[12:15], v[150:153], v[212:215], v[12:15]
	v_mfma_f32_16x16x32_bf16 v[8:11], v[158:161], v[212:215], v[8:11]
	v_mfma_f32_16x16x32_bf16 v[52:55], v[162:165], v[180:183], v[52:55]
	v_mfma_f32_16x16x32_bf16 v[48:51], v[170:173], v[180:183], v[48:51]
	v_mfma_f32_16x16x32_bf16 v[36:39], v[162:165], v[192:195], v[36:39]
	v_mfma_f32_16x16x32_bf16 v[32:35], v[170:173], v[192:195], v[32:35]
	v_mfma_f32_16x16x32_bf16 v[20:23], v[162:165], v[200:203], v[20:23]
	v_mfma_f32_16x16x32_bf16 v[16:19], v[170:173], v[200:203], v[16:19]
	v_mfma_f32_16x16x32_bf16 v[4:7], v[162:165], v[208:211], v[4:7]
	v_mfma_f32_16x16x32_bf16 v[0:3], v[170:173], v[208:211], v[0:3]
	v_mfma_f32_16x16x32_bf16 v[52:55], v[166:169], v[184:187], v[52:55]
	v_mfma_f32_16x16x32_bf16 v[48:51], v[174:177], v[184:187], v[48:51]
	v_mfma_f32_16x16x32_bf16 v[36:39], v[166:169], v[196:199], v[36:39]
	v_mfma_f32_16x16x32_bf16 v[32:35], v[174:177], v[196:199], v[32:35]
	v_mfma_f32_16x16x32_bf16 v[20:23], v[166:169], v[204:207], v[20:23]
	v_mfma_f32_16x16x32_bf16 v[16:19], v[174:177], v[204:207], v[16:19]
	v_mfma_f32_16x16x32_bf16 v[4:7], v[166:169], v[212:215], v[4:7]
	v_mfma_f32_16x16x32_bf16 v[0:3], v[174:177], v[212:215], v[0:3]
	s_setprio 0
	s_barrier
	s_add_i32 s46, s46, 2
	s_add_u32 s44, s44, 0x100
	s_addc_u32 s45, s45, 0
	s_cmpk_gt_u32 s46, 0x55
	s_mov_b64 s[26:27], s[28:29]
	s_cbranch_scc0 .LBB0_263
	s_and_b64 vcc, exec, s[12:13]
	s_cbranch_vccz .LBB0_266
	s_barrier

.LBB0_347:
	ds_read_b128 v[144:147], v153
	ds_read_b128 v[158:161], v153 offset:1024
	ds_read_b128 v[162:165], v153 offset:2048
	ds_read_b128 v[166:169], v153 offset:3072
	ds_read_b128 v[170:173], v154
	ds_read_b128 v[174:177], v154 offset:1024
	ds_read_b128 v[180:183], v154 offset:2048
	ds_read_b128 v[184:187], v154 offset:3072
	s_add_u32 s70, s80, 0xfff80080
	s_addc_u32 s71, s81, -1
	s_cmp_eq_u32 s47, 28
	s_cselect_b32 s85, s13, s71
	s_cselect_b32 s84, s43, s70
	s_cselect_b32 s83, s11, s46
	s_cselect_b32 s82, s44, s45
	v_lshl_add_u64 v[148:149], s[80:81], 0, v[136:137]
	s_add_i32 m0, s22, 0xc000
	ds_read_b128 v[192:195], v155
	ds_read_b128 v[196:199], v155 offset:1024
	ds_read_b128 v[200:203], v155 offset:2048
	ds_read_b128 v[204:207], v155 offset:3072
	ds_read_b128 v[208:211], v155 offset:4096
	ds_read_b128 v[212:215], v155 offset:5120
	ds_read_b128 v[216:219], v155 offset:6144
	ds_read_b128 v[220:223], v155 offset:7168
	global_load_lds_dwordx4 v[148:149], off
	v_lshl_add_u64 v[148:149], s[80:81], 0, v[138:139]
	s_add_i32 m0, s22, 0xe000
	s_nop 0
	global_load_lds_dwordx4 v[148:149], off
	s_waitcnt vmcnt(8)
	s_waitcnt lgkmcnt(0)
	s_barrier
	s_setprio 1
	s_waitcnt lgkmcnt(0)
	v_mfma_f32_16x16x32_bf16 v[124:127], v[144:147], v[192:195], v[124:127]
	v_mfma_f32_16x16x32_bf16 v[120:123], v[162:165], v[192:195], v[120:123]
	v_mfma_f32_16x16x32_bf16 v[108:111], v[144:147], v[200:203], v[108:111]
	v_mfma_f32_16x16x32_bf16 v[104:107], v[162:165], v[200:203], v[104:107]
	v_mfma_f32_16x16x32_bf16 v[92:95], v[144:147], v[208:211], v[92:95]
	v_mfma_f32_16x16x32_bf16 v[88:91], v[162:165], v[208:211], v[88:91]
	v_mfma_f32_16x16x32_bf16 v[76:79], v[144:147], v[216:219], v[76:79]
	v_mfma_f32_16x16x32_bf16 v[72:75], v[162:165], v[216:219], v[72:75]
	v_mfma_f32_16x16x32_bf16 v[124:127], v[158:161], v[196:199], v[124:127]
	v_mfma_f32_16x16x32_bf16 v[120:123], v[166:169], v[196:199], v[120:123]
	v_mfma_f32_16x16x32_bf16 v[108:111], v[158:161], v[204:207], v[108:111]
	v_mfma_f32_16x16x32_bf16 v[104:107], v[166:169], v[204:207], v[104:107]
	v_mfma_f32_16x16x32_bf16 v[92:95], v[158:161], v[212:215], v[92:95]
	v_mfma_f32_16x16x32_bf16 v[88:91], v[166:169], v[212:215], v[88:91]
	v_mfma_f32_16x16x32_bf16 v[76:79], v[158:161], v[220:223], v[76:79]
	v_mfma_f32_16x16x32_bf16 v[72:75], v[166:169], v[220:223], v[72:75]
	v_mfma_f32_16x16x32_bf16 v[116:119], v[170:173], v[192:195], v[116:119]
	v_mfma_f32_16x16x32_bf16 v[112:115], v[180:183], v[192:195], v[112:115]
	v_mfma_f32_16x16x32_bf16 v[100:103], v[170:173], v[200:203], v[100:103]
	v_mfma_f32_16x16x32_bf16 v[96:99], v[180:183], v[200:203], v[96:99]
	v_mfma_f32_16x16x32_bf16 v[84:87], v[170:173], v[208:211], v[84:87]
	v_mfma_f32_16x16x32_bf16 v[80:83], v[180:183], v[208:211], v[80:83]
	v_mfma_f32_16x16x32_bf16 v[68:71], v[170:173], v[216:219], v[68:71]
	v_mfma_f32_16x16x32_bf16 v[64:67], v[180:183], v[216:219], v[64:67]
	v_mfma_f32_16x16x32_bf16 v[116:119], v[174:177], v[196:199], v[116:119]
	v_mfma_f32_16x16x32_bf16 v[112:115], v[184:187], v[196:199], v[112:115]
	v_mfma_f32_16x16x32_bf16 v[100:103], v[174:177], v[204:207], v[100:103]
	v_mfma_f32_16x16x32_bf16 v[96:99], v[184:187], v[204:207], v[96:99]
	v_mfma_f32_16x16x32_bf16 v[84:87], v[174:177], v[212:215], v[84:87]
	v_mfma_f32_16x16x32_bf16 v[80:83], v[184:187], v[212:215], v[80:83]
	v_mfma_f32_16x16x32_bf16 v[68:71], v[174:177], v[220:223], v[68:71]
	v_mfma_f32_16x16x32_bf16 v[64:67], v[184:187], v[220:223], v[64:67]
	s_setprio 0
	s_barrier
	s_add_i32 s70, s37, s20
	v_lshl_add_u64 v[148:149], s[82:83], 0, v[132:133]
	s_mov_b32 m0, s70
	ds_read_b128 v[192:195], v155 offset:16384
	ds_read_b128 v[196:199], v155 offset:17408
	ds_read_b128 v[200:203], v155 offset:18432
	ds_read_b128 v[204:207], v155 offset:19456
	ds_read_b128 v[208:211], v155 offset:20480
	ds_read_b128 v[212:215], v155 offset:21504
	ds_read_b128 v[216:219], v155 offset:22528
	ds_read_b128 v[220:223], v155 offset:23552
	global_load_lds_dwordx4 v[148:149], off
	s_add_i32 m0, s70, 0x2000
	s_add_u32 s70, s82, 0x80000
	v_lshl_add_u64 v[188:189], s[82:83], 0, v[128:129]
	s_addc_u32 s71, s83, 0
	s_add_i32 s72, s38, s20
	global_load_lds_dwordx4 v[188:189], off
	v_lshl_add_u64 v[224:225], s[70:71], 0, v[132:133]
	s_mov_b32 m0, s72
	v_lshl_add_u64 v[226:227], s[84:85], 0, v[130:131]
	global_load_lds_dwordx4 v[224:225], off
	v_lshl_add_u64 v[224:225], s[70:71], 0, v[128:129]
	s_add_i32 m0, s72, 0x2000
	s_nop 0
	global_load_lds_dwordx4 v[224:225], off
	v_lshl_add_u64 v[224:225], s[84:85], 0, v[134:135]
	s_mov_b32 m0, s22
	s_nop 0
	global_load_lds_dwordx4 v[224:225], off
	s_mov_b32 m0, s23
	s_nop 0
	global_load_lds_dwordx4 v[226:227], off
	s_waitcnt vmcnt(8)
	s_waitcnt lgkmcnt(0)
	s_barrier
	s_setprio 1
	s_waitcnt lgkmcnt(0)
	v_mfma_f32_16x16x32_bf16 v[60:63], v[144:147], v[192:195], v[60:63]
	v_mfma_f32_16x16x32_bf16 v[56:59], v[162:165], v[192:195], v[56:59]
	v_mfma_f32_16x16x32_bf16 v[44:47], v[144:147], v[200:203], v[44:47]
	v_mfma_f32_16x16x32_bf16 v[40:43], v[162:165], v[200:203], v[40:43]
	v_mfma_f32_16x16x32_bf16 v[28:31], v[144:147], v[208:211], v[28:31]
	v_mfma_f32_16x16x32_bf16 v[24:27], v[162:165], v[208:211], v[24:27]
	v_mfma_f32_16x16x32_bf16 v[12:15], v[144:147], v[216:219], v[12:15]
	v_mfma_f32_16x16x32_bf16 v[8:11], v[162:165], v[216:219], v[8:11]
	v_mfma_f32_16x16x32_bf16 v[60:63], v[158:161], v[196:199], v[60:63]
	v_mfma_f32_16x16x32_bf16 v[56:59], v[166:169], v[196:199], v[56:59]
	v_mfma_f32_16x16x32_bf16 v[44:47], v[158:161], v[204:207], v[44:47]
	v_mfma_f32_16x16x32_bf16 v[40:43], v[166:169], v[204:207], v[40:43]
	v_mfma_f32_16x16x32_bf16 v[28:31], v[158:161], v[212:215], v[28:31]
	v_mfma_f32_16x16x32_bf16 v[24:27], v[166:169], v[212:215], v[24:27]
	v_mfma_f32_16x16x32_bf16 v[12:15], v[158:161], v[220:223], v[12:15]
	v_mfma_f32_16x16x32_bf16 v[8:11], v[166:169], v[220:223], v[8:11]
	v_mfma_f32_16x16x32_bf16 v[52:55], v[170:173], v[192:195], v[52:55]
	v_mfma_f32_16x16x32_bf16 v[48:51], v[180:183], v[192:195], v[48:51]
	v_mfma_f32_16x16x32_bf16 v[36:39], v[170:173], v[200:203], v[36:39]
	v_mfma_f32_16x16x32_bf16 v[32:35], v[180:183], v[200:203], v[32:35]
	v_mfma_f32_16x16x32_bf16 v[20:23], v[170:173], v[208:211], v[20:23]
	v_mfma_f32_16x16x32_bf16 v[16:19], v[180:183], v[208:211], v[16:19]
	v_mfma_f32_16x16x32_bf16 v[4:7], v[170:173], v[216:219], v[4:7]
	v_mfma_f32_16x16x32_bf16 v[0:3], v[180:183], v[216:219], v[0:3]
	v_mfma_f32_16x16x32_bf16 v[52:55], v[174:177], v[196:199], v[52:55]
	v_mfma_f32_16x16x32_bf16 v[48:51], v[184:187], v[196:199], v[48:51]
	v_mfma_f32_16x16x32_bf16 v[36:39], v[174:177], v[204:207], v[36:39]
	v_mfma_f32_16x16x32_bf16 v[32:35], v[184:187], v[204:207], v[32:35]
	v_mfma_f32_16x16x32_bf16 v[20:23], v[174:177], v[212:215], v[20:23]
	v_mfma_f32_16x16x32_bf16 v[16:19], v[184:187], v[212:215], v[16:19]
	v_mfma_f32_16x16x32_bf16 v[4:7], v[174:177], v[220:223], v[4:7]
	v_mfma_f32_16x16x32_bf16 v[0:3], v[184:187], v[220:223], v[0:3]
	s_setprio 0
	s_barrier
	s_add_i32 s72, 0, 0x18000
	v_add_u32_e32 v157, s72, v151
	s_add_i32 s73, 0, 0x1c000
	ds_read_b128 v[144:147], v157
	ds_read_b128 v[158:161], v157 offset:1024
	ds_read_b128 v[162:165], v157 offset:2048
	ds_read_b128 v[166:169], v157 offset:3072
	v_add_u32_e32 v157, s73, v151
	ds_read_b128 v[170:173], v157
	ds_read_b128 v[174:177], v157 offset:1024
	ds_read_b128 v[180:183], v157 offset:2048
	ds_read_b128 v[184:187], v157 offset:3072
	s_add_u32 s70, s84, 0x80000
	s_addc_u32 s71, s85, 0
	s_mov_b32 m0, s24
	v_lshl_add_u64 v[228:229], s[70:71], 0, v[134:135]
	ds_read_b128 v[192:195], v155 offset:32768
	ds_read_b128 v[196:199], v155 offset:33792
	ds_read_b128 v[200:203], v155 offset:34816
	ds_read_b128 v[204:207], v155 offset:35840
	ds_read_b128 v[208:211], v155 offset:36864
	ds_read_b128 v[212:215], v155 offset:37888
	ds_read_b128 v[216:219], v155 offset:38912
	ds_read_b128 v[220:223], v155 offset:39936
	global_load_lds_dwordx4 v[228:229], off
	v_lshl_add_u64 v[228:229], s[70:71], 0, v[130:131]
	s_mov_b32 m0, s25
	s_nop 0
	global_load_lds_dwordx4 v[228:229], off
	s_waitcnt vmcnt(8)
	s_waitcnt lgkmcnt(0)
	s_barrier
	s_setprio 1
	s_waitcnt lgkmcnt(0)
	v_mfma_f32_16x16x32_bf16 v[124:127], v[144:147], v[192:195], v[124:127]
	v_mfma_f32_16x16x32_bf16 v[120:123], v[162:165], v[192:195], v[120:123]
	v_mfma_f32_16x16x32_bf16 v[108:111], v[144:147], v[200:203], v[108:111]
	v_mfma_f32_16x16x32_bf16 v[104:107], v[162:165], v[200:203], v[104:107]
	v_mfma_f32_16x16x32_bf16 v[92:95], v[144:147], v[208:211], v[92:95]
	v_mfma_f32_16x16x32_bf16 v[88:91], v[162:165], v[208:211], v[88:91]
	v_mfma_f32_16x16x32_bf16 v[76:79], v[144:147], v[216:219], v[76:79]
	v_mfma_f32_16x16x32_bf16 v[72:75], v[162:165], v[216:219], v[72:75]
	v_mfma_f32_16x16x32_bf16 v[124:127], v[158:161], v[196:199], v[124:127]
	v_mfma_f32_16x16x32_bf16 v[120:123], v[166:169], v[196:199], v[120:123]
	v_mfma_f32_16x16x32_bf16 v[108:111], v[158:161], v[204:207], v[108:111]
	v_mfma_f32_16x16x32_bf16 v[104:107], v[166:169], v[204:207], v[104:107]
	v_mfma_f32_16x16x32_bf16 v[92:95], v[158:161], v[212:215], v[92:95]
	v_mfma_f32_16x16x32_bf16 v[88:91], v[166:169], v[212:215], v[88:91]
	v_mfma_f32_16x16x32_bf16 v[76:79], v[158:161], v[220:223], v[76:79]
	v_mfma_f32_16x16x32_bf16 v[72:75], v[166:169], v[220:223], v[72:75]
	v_mfma_f32_16x16x32_bf16 v[116:119], v[170:173], v[192:195], v[116:119]
	v_mfma_f32_16x16x32_bf16 v[112:115], v[180:183], v[192:195], v[112:115]
	v_mfma_f32_16x16x32_bf16 v[100:103], v[170:173], v[200:203], v[100:103]
	v_mfma_f32_16x16x32_bf16 v[96:99], v[180:183], v[200:203], v[96:99]
	v_mfma_f32_16x16x32_bf16 v[84:87], v[170:173], v[208:211], v[84:87]
	v_mfma_f32_16x16x32_bf16 v[80:83], v[180:183], v[208:211], v[80:83]
	v_mfma_f32_16x16x32_bf16 v[68:71], v[170:173], v[216:219], v[68:71]
	v_mfma_f32_16x16x32_bf16 v[64:67], v[180:183], v[216:219], v[64:67]
	v_mfma_f32_16x16x32_bf16 v[116:119], v[174:177], v[196:199], v[116:119]
	v_mfma_f32_16x16x32_bf16 v[112:115], v[184:187], v[196:199], v[112:115]
	v_mfma_f32_16x16x32_bf16 v[100:103], v[174:177], v[204:207], v[100:103]
	v_mfma_f32_16x16x32_bf16 v[96:99], v[184:187], v[204:207], v[96:99]
	v_mfma_f32_16x16x32_bf16 v[84:87], v[174:177], v[212:215], v[84:87]
	v_mfma_f32_16x16x32_bf16 v[80:83], v[184:187], v[212:215], v[80:83]
	v_mfma_f32_16x16x32_bf16 v[68:71], v[174:177], v[220:223], v[68:71]
	v_mfma_f32_16x16x32_bf16 v[64:67], v[184:187], v[220:223], v[64:67]
	s_setprio 0
	s_barrier
	s_add_i32 s70, s72, s20
	v_lshl_add_u64 v[148:149], v[148:149], 0, s[6:7]
	s_mov_b32 m0, s70
	ds_read_b128 v[192:195], v155 offset:49152
	ds_read_b128 v[196:199], v155 offset:50176
	ds_read_b128 v[200:203], v155 offset:51200
	ds_read_b128 v[204:207], v155 offset:52224
	ds_read_b128 v[208:211], v155 offset:53248
	ds_read_b128 v[212:215], v155 offset:54272
	ds_read_b128 v[216:219], v155 offset:55296
	ds_read_b128 v[220:223], v155 offset:56320
	global_load_lds_dwordx4 v[148:149], off
	s_add_i32 m0, s70, 0x2000
	s_add_u32 s70, s82, 0x80080
	v_lshl_add_u64 v[148:149], v[188:189], 0, s[6:7]
	s_addc_u32 s71, s83, 0
	s_add_i32 s72, s73, s20
	global_load_lds_dwordx4 v[148:149], off
	v_lshl_add_u64 v[148:149], s[70:71], 0, v[132:133]
	s_mov_b32 m0, s72
	s_nop 0
	global_load_lds_dwordx4 v[148:149], off
	v_lshl_add_u64 v[148:149], s[70:71], 0, v[128:129]
	s_add_i32 m0, s72, 0x2000
	s_nop 0
	global_load_lds_dwordx4 v[148:149], off
	v_lshl_add_u64 v[148:149], v[224:225], 0, s[6:7]
	s_mov_b32 m0, s35
	s_nop 0
	global_load_lds_dwordx4 v[148:149], off
	v_lshl_add_u64 v[148:149], v[226:227], 0, s[6:7]
	s_mov_b32 m0, s36
	s_nop 0
	global_load_lds_dwordx4 v[148:149], off
	s_waitcnt vmcnt(8)
	s_waitcnt lgkmcnt(0)
	s_barrier
	s_setprio 1
	s_waitcnt lgkmcnt(0)
	v_mfma_f32_16x16x32_bf16 v[60:63], v[144:147], v[192:195], v[60:63]
	v_mfma_f32_16x16x32_bf16 v[56:59], v[162:165], v[192:195], v[56:59]
	v_mfma_f32_16x16x32_bf16 v[44:47], v[144:147], v[200:203], v[44:47]
	v_mfma_f32_16x16x32_bf16 v[40:43], v[162:165], v[200:203], v[40:43]
	v_mfma_f32_16x16x32_bf16 v[28:31], v[144:147], v[208:211], v[28:31]
	v_mfma_f32_16x16x32_bf16 v[24:27], v[162:165], v[208:211], v[24:27]
	v_mfma_f32_16x16x32_bf16 v[12:15], v[144:147], v[216:219], v[12:15]
	v_mfma_f32_16x16x32_bf16 v[8:11], v[162:165], v[216:219], v[8:11]
	v_mfma_f32_16x16x32_bf16 v[60:63], v[158:161], v[196:199], v[60:63]
	v_mfma_f32_16x16x32_bf16 v[56:59], v[166:169], v[196:199], v[56:59]
	v_mfma_f32_16x16x32_bf16 v[44:47], v[158:161], v[204:207], v[44:47]
	v_mfma_f32_16x16x32_bf16 v[40:43], v[166:169], v[204:207], v[40:43]
	v_mfma_f32_16x16x32_bf16 v[28:31], v[158:161], v[212:215], v[28:31]
	v_mfma_f32_16x16x32_bf16 v[24:27], v[166:169], v[212:215], v[24:27]
	v_mfma_f32_16x16x32_bf16 v[12:15], v[158:161], v[220:223], v[12:15]
	v_mfma_f32_16x16x32_bf16 v[8:11], v[166:169], v[220:223], v[8:11]
	v_mfma_f32_16x16x32_bf16 v[52:55], v[170:173], v[192:195], v[52:55]
	v_mfma_f32_16x16x32_bf16 v[48:51], v[180:183], v[192:195], v[48:51]
	v_mfma_f32_16x16x32_bf16 v[36:39], v[170:173], v[200:203], v[36:39]
	v_mfma_f32_16x16x32_bf16 v[32:35], v[180:183], v[200:203], v[32:35]
	v_mfma_f32_16x16x32_bf16 v[20:23], v[170:173], v[208:211], v[20:23]
	v_mfma_f32_16x16x32_bf16 v[16:19], v[180:183], v[208:211], v[16:19]
	v_mfma_f32_16x16x32_bf16 v[4:7], v[170:173], v[216:219], v[4:7]
	v_mfma_f32_16x16x32_bf16 v[0:3], v[180:183], v[216:219], v[0:3]
	v_mfma_f32_16x16x32_bf16 v[52:55], v[174:177], v[196:199], v[52:55]
	v_mfma_f32_16x16x32_bf16 v[48:51], v[184:187], v[196:199], v[48:51]
	v_mfma_f32_16x16x32_bf16 v[36:39], v[174:177], v[204:207], v[36:39]
	v_mfma_f32_16x16x32_bf16 v[32:35], v[184:187], v[204:207], v[32:35]
	v_mfma_f32_16x16x32_bf16 v[20:23], v[174:177], v[212:215], v[20:23]
	v_mfma_f32_16x16x32_bf16 v[16:19], v[184:187], v[212:215], v[16:19]
	v_mfma_f32_16x16x32_bf16 v[4:7], v[174:177], v[220:223], v[4:7]
	v_mfma_f32_16x16x32_bf16 v[0:3], v[184:187], v[220:223], v[0:3]
	s_setprio 0
	s_barrier
	s_add_i32 s47, s47, 2
	s_add_u32 s80, s80, 0x100
	s_addc_u32 s81, s81, 0
	s_add_u32 s45, s45, 0x100
	s_addc_u32 s46, s46, 0
	s_cmp_gt_u32 s47, 29
	s_cbranch_scc0 .LBB0_347
	s_and_b64 vcc, exec, s[8:9]
	s_cbranch_vccz .LBB0_350
	s_barrier

.LBB0_429:
	ds_read_b128 v[0:3], v145
	ds_read_b128 v[4:7], v145 offset:1024
	ds_read_b128 v[8:11], v145 offset:2048
	ds_read_b128 v[12:15], v145 offset:3072
	ds_read_b128 v[16:19], v146
	ds_read_b128 v[20:23], v146 offset:1024
	ds_read_b128 v[24:27], v146 offset:2048
	ds_read_b128 v[28:31], v146 offset:3072
	s_ashr_i32 s31, s30, 31
	s_lshl_b64 s[42:43], s[30:31], 17
	s_add_u32 s80, s52, s42
	s_addc_u32 s81, s53, s43
	s_and_b64 s[42:43], s[4:5], exec
	s_cselect_b32 s83, s81, s91
	s_cselect_b32 s82, s80, s90
	s_ashr_i32 s29, s28, 31
	s_lshl_b64 s[42:43], s[28:29], 17
	s_add_u32 s84, s54, s42
	s_addc_u32 s85, s55, s43
	s_and_b64 s[42:43], s[4:5], exec
	s_cselect_b32 vcc_hi, s85, s93
	s_cselect_b32 vcc_lo, s84, s92
	s_add_u32 s42, s90, 0x10080
	s_addc_u32 s43, s91, 0
	s_add_i32 s46, s21, 0xc000
	v_lshl_add_u64 v[64:65], s[42:43], 0, v[128:129]
	s_mov_b32 m0, s46
	s_add_i32 s29, s21, 0xe000
	ds_read_b128 v[32:35], v147
	ds_read_b128 v[36:39], v147 offset:1024
	ds_read_b128 v[40:43], v147 offset:2048
	ds_read_b128 v[44:47], v147 offset:3072
	ds_read_b128 v[48:51], v147 offset:4096
	ds_read_b128 v[52:55], v147 offset:5120
	ds_read_b128 v[56:59], v147 offset:6144
	ds_read_b128 v[60:63], v147 offset:7168
	global_load_lds_dwordx4 v[64:65], off
	v_lshl_add_u64 v[64:65], s[42:43], 0, v[130:131]
	s_mov_b32 m0, s29
	s_nop 0
	global_load_lds_dwordx4 v[64:65], off
	s_waitcnt vmcnt(8)
	s_waitcnt lgkmcnt(0)
	s_barrier
	s_setprio 1
	s_waitcnt lgkmcnt(0)
	v_mfma_f32_16x16x32_bf16 v[64:67], v[0:3], v[32:35], 0
	v_mfma_f32_16x16x32_bf16 v[68:71], v[8:11], v[32:35], 0
	v_mfma_f32_16x16x32_bf16 v[72:75], v[0:3], v[40:43], 0
	v_mfma_f32_16x16x32_bf16 v[76:79], v[8:11], v[40:43], 0
	v_mfma_f32_16x16x32_bf16 v[80:83], v[0:3], v[48:51], 0
	v_mfma_f32_16x16x32_bf16 v[84:87], v[8:11], v[48:51], 0
	v_mfma_f32_16x16x32_bf16 v[88:91], v[0:3], v[56:59], 0
	v_mfma_f32_16x16x32_bf16 v[92:95], v[8:11], v[56:59], 0
	v_mfma_f32_16x16x32_bf16 v[64:67], v[4:7], v[36:39], v[64:67]
	v_mfma_f32_16x16x32_bf16 v[68:71], v[12:15], v[36:39], v[68:71]
	v_mfma_f32_16x16x32_bf16 v[72:75], v[4:7], v[44:47], v[72:75]
	v_mfma_f32_16x16x32_bf16 v[76:79], v[12:15], v[44:47], v[76:79]
	v_mfma_f32_16x16x32_bf16 v[80:83], v[4:7], v[52:55], v[80:83]
	v_mfma_f32_16x16x32_bf16 v[84:87], v[12:15], v[52:55], v[84:87]
	v_mfma_f32_16x16x32_bf16 v[88:91], v[4:7], v[60:63], v[88:91]
	v_mfma_f32_16x16x32_bf16 v[92:95], v[12:15], v[60:63], v[92:95]
	v_mfma_f32_16x16x32_bf16 v[96:99], v[16:19], v[32:35], 0
	v_mfma_f32_16x16x32_bf16 v[32:35], v[24:27], v[32:35], 0
	v_mfma_f32_16x16x32_bf16 v[96:99], v[20:23], v[36:39], v[96:99]
	v_mfma_f32_16x16x32_bf16 v[32:35], v[28:31], v[36:39], v[32:35]
	v_mfma_f32_16x16x32_bf16 v[36:39], v[16:19], v[40:43], 0
	v_mfma_f32_16x16x32_bf16 v[40:43], v[24:27], v[40:43], 0
	v_mfma_f32_16x16x32_bf16 v[36:39], v[20:23], v[44:47], v[36:39]
	v_mfma_f32_16x16x32_bf16 v[40:43], v[28:31], v[44:47], v[40:43]
	v_mfma_f32_16x16x32_bf16 v[44:47], v[16:19], v[48:51], 0
	v_mfma_f32_16x16x32_bf16 v[48:51], v[24:27], v[48:51], 0
	v_mfma_f32_16x16x32_bf16 v[44:47], v[20:23], v[52:55], v[44:47]
	v_mfma_f32_16x16x32_bf16 v[48:51], v[28:31], v[52:55], v[48:51]
	v_mfma_f32_16x16x32_bf16 v[52:55], v[16:19], v[56:59], 0
	v_mfma_f32_16x16x32_bf16 v[56:59], v[24:27], v[56:59], 0
	v_mfma_f32_16x16x32_bf16 v[52:55], v[20:23], v[60:63], v[52:55]
	v_mfma_f32_16x16x32_bf16 v[56:59], v[28:31], v[60:63], v[56:59]
	s_setprio 0
	s_barrier
	s_add_i32 s44, s35, s20
	v_lshl_add_u64 v[188:189], s[92:93], 0, v[128:129]
	s_add_i32 s31, s44, 0x2000
	v_lshl_add_u64 v[138:139], v[188:189], 0, s[14:15]
	s_mov_b32 m0, s44
	v_lshl_add_u64 v[216:217], s[92:93], 0, v[130:131]
	s_add_u32 s70, s92, 0x10100
	ds_read_b128 v[60:63], v147 offset:16384
	ds_read_b128 v[100:103], v147 offset:17408
	ds_read_b128 v[104:107], v147 offset:18432
	ds_read_b128 v[108:111], v147 offset:19456
	ds_read_b128 v[112:115], v147 offset:20480
	ds_read_b128 v[116:119], v147 offset:21504
	ds_read_b128 v[120:123], v147 offset:22528
	ds_read_b128 v[124:127], v147 offset:23552
	global_load_lds_dwordx4 v[138:139], off
	v_lshl_add_u64 v[138:139], v[216:217], 0, s[14:15]
	s_mov_b32 m0, s31
	s_addc_u32 s71, s93, 0
	s_add_i32 s42, s36, s20
	global_load_lds_dwordx4 v[138:139], off
	v_lshl_add_u64 v[138:139], s[70:71], 0, v[128:129]
	s_mov_b32 m0, s42
	s_add_i32 s43, s42, 0x2000
	global_load_lds_dwordx4 v[138:139], off
	v_lshl_add_u64 v[138:139], s[70:71], 0, v[130:131]
	s_mov_b32 m0, s43
	v_lshl_add_u64 v[218:219], s[90:91], 0, v[128:129]
	global_load_lds_dwordx4 v[138:139], off
	v_lshl_add_u64 v[138:139], v[218:219], 0, s[14:15]
	s_mov_b32 m0, s21
	v_lshl_add_u64 v[220:221], s[90:91], 0, v[130:131]
	global_load_lds_dwordx4 v[138:139], off
	v_lshl_add_u64 v[138:139], v[220:221], 0, s[14:15]
	s_mov_b32 m0, s22
	s_nop 0
	global_load_lds_dwordx4 v[138:139], off
	s_waitcnt vmcnt(8)
	s_waitcnt lgkmcnt(0)
	s_barrier
	s_setprio 1
	s_waitcnt lgkmcnt(0)
	v_mfma_f32_16x16x32_bf16 v[138:141], v[0:3], v[60:63], 0
	v_mfma_f32_16x16x32_bf16 v[154:157], v[0:3], v[104:107], 0
	v_mfma_f32_16x16x32_bf16 v[162:165], v[0:3], v[112:115], 0
	v_mfma_f32_16x16x32_bf16 v[0:3], v[0:3], v[120:123], 0
	v_mfma_f32_16x16x32_bf16 v[138:141], v[4:7], v[100:103], v[138:141]
	v_mfma_f32_16x16x32_bf16 v[154:157], v[4:7], v[108:111], v[154:157]
	v_mfma_f32_16x16x32_bf16 v[162:165], v[4:7], v[116:119], v[162:165]
	v_mfma_f32_16x16x32_bf16 v[0:3], v[4:7], v[124:127], v[0:3]
	v_mfma_f32_16x16x32_bf16 v[4:7], v[8:11], v[120:123], 0
	v_mfma_f32_16x16x32_bf16 v[150:153], v[8:11], v[60:63], 0
	v_mfma_f32_16x16x32_bf16 v[158:161], v[8:11], v[104:107], 0
	v_mfma_f32_16x16x32_bf16 v[166:169], v[8:11], v[112:115], 0
	v_mfma_f32_16x16x32_bf16 v[4:7], v[12:15], v[124:127], v[4:7]
	v_mfma_f32_16x16x32_bf16 v[150:153], v[12:15], v[100:103], v[150:153]
	v_mfma_f32_16x16x32_bf16 v[158:161], v[12:15], v[108:111], v[158:161]
	v_mfma_f32_16x16x32_bf16 v[166:169], v[12:15], v[116:119], v[166:169]
	v_mfma_f32_16x16x32_bf16 v[8:11], v[16:19], v[60:63], 0
	v_mfma_f32_16x16x32_bf16 v[12:15], v[24:27], v[60:63], 0
	v_mfma_f32_16x16x32_bf16 v[8:11], v[20:23], v[100:103], v[8:11]
	v_mfma_f32_16x16x32_bf16 v[12:15], v[28:31], v[100:103], v[12:15]
	v_mfma_f32_16x16x32_bf16 v[60:63], v[16:19], v[104:107], 0
	v_mfma_f32_16x16x32_bf16 v[100:103], v[24:27], v[104:107], 0
	v_mfma_f32_16x16x32_bf16 v[104:107], v[16:19], v[112:115], 0
	v_mfma_f32_16x16x32_bf16 v[16:19], v[16:19], v[120:123], 0
	v_mfma_f32_16x16x32_bf16 v[60:63], v[20:23], v[108:111], v[60:63]
	v_mfma_f32_16x16x32_bf16 v[100:103], v[28:31], v[108:111], v[100:103]
	v_mfma_f32_16x16x32_bf16 v[104:107], v[20:23], v[116:119], v[104:107]
	v_mfma_f32_16x16x32_bf16 v[108:111], v[24:27], v[112:115], 0
	v_mfma_f32_16x16x32_bf16 v[16:19], v[20:23], v[124:127], v[16:19]
	v_mfma_f32_16x16x32_bf16 v[20:23], v[24:27], v[120:123], 0
	v_mfma_f32_16x16x32_bf16 v[108:111], v[28:31], v[116:119], v[108:111]
	v_mfma_f32_16x16x32_bf16 v[20:23], v[28:31], v[124:127], v[20:23]
	s_setprio 0
	s_barrier
	s_add_i32 s45, 0, 0x18000
	s_add_i32 s47, 0, 0x1c000
	v_add_u32_e32 v132, s45, v143
	v_add_u32_e32 v149, s47, v143
	ds_read_b128 v[24:27], v132
	ds_read_b128 v[28:31], v132 offset:1024
	ds_read_b128 v[112:115], v132 offset:2048
	ds_read_b128 v[116:119], v132 offset:3072
	ds_read_b128 v[120:123], v149
	ds_read_b128 v[124:127], v149 offset:1024
	ds_read_b128 v[170:173], v149 offset:2048
	ds_read_b128 v[174:177], v149 offset:3072
	s_add_u32 s70, s90, 0x10100
	s_addc_u32 s71, s91, 0
	s_mov_b32 m0, s23
	v_lshl_add_u64 v[222:223], s[70:71], 0, v[128:129]
	ds_read_b128 v[180:183], v147 offset:32768
	ds_read_b128 v[184:187], v147 offset:33792
	ds_read_b128 v[192:195], v147 offset:34816
	ds_read_b128 v[196:199], v147 offset:35840
	ds_read_b128 v[200:203], v147 offset:36864
	ds_read_b128 v[204:207], v147 offset:37888
	ds_read_b128 v[208:211], v147 offset:38912
	ds_read_b128 v[212:215], v147 offset:39936
	global_load_lds_dwordx4 v[222:223], off
	v_lshl_add_u64 v[222:223], s[70:71], 0, v[130:131]
	s_mov_b32 m0, s24
	s_nop 0
	global_load_lds_dwordx4 v[222:223], off
	s_waitcnt vmcnt(8)
	s_waitcnt lgkmcnt(0)
	s_barrier
	s_setprio 1
	s_waitcnt lgkmcnt(0)
	v_mfma_f32_16x16x32_bf16 v[64:67], v[24:27], v[180:183], v[64:67]
	v_mfma_f32_16x16x32_bf16 v[68:71], v[112:115], v[180:183], v[68:71]
	v_mfma_f32_16x16x32_bf16 v[72:75], v[24:27], v[192:195], v[72:75]
	v_mfma_f32_16x16x32_bf16 v[76:79], v[112:115], v[192:195], v[76:79]
	v_mfma_f32_16x16x32_bf16 v[80:83], v[24:27], v[200:203], v[80:83]
	v_mfma_f32_16x16x32_bf16 v[84:87], v[112:115], v[200:203], v[84:87]
	v_mfma_f32_16x16x32_bf16 v[88:91], v[24:27], v[208:211], v[88:91]
	v_mfma_f32_16x16x32_bf16 v[92:95], v[112:115], v[208:211], v[92:95]
	v_mfma_f32_16x16x32_bf16 v[64:67], v[28:31], v[184:187], v[64:67]
	v_mfma_f32_16x16x32_bf16 v[68:71], v[116:119], v[184:187], v[68:71]
	v_mfma_f32_16x16x32_bf16 v[72:75], v[28:31], v[196:199], v[72:75]
	v_mfma_f32_16x16x32_bf16 v[76:79], v[116:119], v[196:199], v[76:79]
	v_mfma_f32_16x16x32_bf16 v[80:83], v[28:31], v[204:207], v[80:83]
	v_mfma_f32_16x16x32_bf16 v[84:87], v[116:119], v[204:207], v[84:87]
	v_mfma_f32_16x16x32_bf16 v[88:91], v[28:31], v[212:215], v[88:91]
	v_mfma_f32_16x16x32_bf16 v[92:95], v[116:119], v[212:215], v[92:95]
	v_mfma_f32_16x16x32_bf16 v[96:99], v[120:123], v[180:183], v[96:99]
	v_mfma_f32_16x16x32_bf16 v[32:35], v[170:173], v[180:183], v[32:35]
	v_mfma_f32_16x16x32_bf16 v[36:39], v[120:123], v[192:195], v[36:39]
	v_mfma_f32_16x16x32_bf16 v[40:43], v[170:173], v[192:195], v[40:43]
	v_mfma_f32_16x16x32_bf16 v[44:47], v[120:123], v[200:203], v[44:47]
	v_mfma_f32_16x16x32_bf16 v[48:51], v[170:173], v[200:203], v[48:51]
	v_mfma_f32_16x16x32_bf16 v[52:55], v[120:123], v[208:211], v[52:55]
	v_mfma_f32_16x16x32_bf16 v[56:59], v[170:173], v[208:211], v[56:59]
	v_mfma_f32_16x16x32_bf16 v[96:99], v[124:127], v[184:187], v[96:99]
	v_mfma_f32_16x16x32_bf16 v[32:35], v[174:177], v[184:187], v[32:35]
	v_mfma_f32_16x16x32_bf16 v[36:39], v[124:127], v[196:199], v[36:39]
	v_mfma_f32_16x16x32_bf16 v[40:43], v[174:177], v[196:199], v[40:43]
	v_mfma_f32_16x16x32_bf16 v[44:47], v[124:127], v[204:207], v[44:47]
	v_mfma_f32_16x16x32_bf16 v[48:51], v[174:177], v[204:207], v[48:51]
	v_mfma_f32_16x16x32_bf16 v[52:55], v[124:127], v[212:215], v[52:55]
	v_mfma_f32_16x16x32_bf16 v[56:59], v[174:177], v[212:215], v[56:59]
	s_setprio 0
	s_barrier
	s_add_i32 s71, s45, s20
	s_add_i32 s45, s71, 0x2000
	v_lshl_add_u64 v[188:189], v[188:189], 0, s[26:27]
	s_mov_b32 m0, s71
	s_add_u32 s72, s92, 0x10180
	ds_read_b128 v[180:183], v147 offset:49152
	ds_read_b128 v[184:187], v147 offset:50176
	ds_read_b128 v[192:195], v147 offset:51200
	ds_read_b128 v[196:199], v147 offset:52224
	ds_read_b128 v[200:203], v147 offset:53248
	ds_read_b128 v[204:207], v147 offset:54272
	ds_read_b128 v[208:211], v147 offset:55296
	ds_read_b128 v[212:215], v147 offset:56320
	global_load_lds_dwordx4 v[188:189], off
	v_lshl_add_u64 v[188:189], v[216:217], 0, s[26:27]
	s_mov_b32 m0, s45
	s_addc_u32 s73, s93, 0
	s_add_i32 s47, s47, s20
	global_load_lds_dwordx4 v[188:189], off
	v_lshl_add_u64 v[188:189], s[72:73], 0, v[128:129]
	s_mov_b32 m0, s47
	s_add_i32 s70, s47, 0x2000
	global_load_lds_dwordx4 v[188:189], off
	v_lshl_add_u64 v[188:189], s[72:73], 0, v[130:131]
	s_mov_b32 m0, s70
	s_nop 0
	global_load_lds_dwordx4 v[188:189], off
	v_lshl_add_u64 v[188:189], v[218:219], 0, s[26:27]
	s_mov_b32 m0, s25
	s_nop 0
	global_load_lds_dwordx4 v[188:189], off
	v_lshl_add_u64 v[188:189], v[220:221], 0, s[26:27]
	s_mov_b32 m0, s33
	s_nop 0
	global_load_lds_dwordx4 v[188:189], off
	s_waitcnt vmcnt(8)
	s_waitcnt lgkmcnt(0)
	s_barrier
	s_setprio 1
	s_waitcnt lgkmcnt(0)
	v_mfma_f32_16x16x32_bf16 v[0:3], v[24:27], v[208:211], v[0:3]
	v_mfma_f32_16x16x32_bf16 v[4:7], v[112:115], v[208:211], v[4:7]
	v_mfma_f32_16x16x32_bf16 v[138:141], v[24:27], v[180:183], v[138:141]
	v_mfma_f32_16x16x32_bf16 v[150:153], v[112:115], v[180:183], v[150:153]
	v_mfma_f32_16x16x32_bf16 v[154:157], v[24:27], v[192:195], v[154:157]
	v_mfma_f32_16x16x32_bf16 v[158:161], v[112:115], v[192:195], v[158:161]
	v_mfma_f32_16x16x32_bf16 v[162:165], v[24:27], v[200:203], v[162:165]
	v_mfma_f32_16x16x32_bf16 v[166:169], v[112:115], v[200:203], v[166:169]
	v_mfma_f32_16x16x32_bf16 v[0:3], v[28:31], v[212:215], v[0:3]
	v_mfma_f32_16x16x32_bf16 v[4:7], v[116:119], v[212:215], v[4:7]
	v_mfma_f32_16x16x32_bf16 v[138:141], v[28:31], v[184:187], v[138:141]
	v_mfma_f32_16x16x32_bf16 v[150:153], v[116:119], v[184:187], v[150:153]
	v_mfma_f32_16x16x32_bf16 v[154:157], v[28:31], v[196:199], v[154:157]
	v_mfma_f32_16x16x32_bf16 v[158:161], v[116:119], v[196:199], v[158:161]
	v_mfma_f32_16x16x32_bf16 v[162:165], v[28:31], v[204:207], v[162:165]
	v_mfma_f32_16x16x32_bf16 v[166:169], v[116:119], v[204:207], v[166:169]
	v_mfma_f32_16x16x32_bf16 v[8:11], v[120:123], v[180:183], v[8:11]
	v_mfma_f32_16x16x32_bf16 v[12:15], v[170:173], v[180:183], v[12:15]
	v_mfma_f32_16x16x32_bf16 v[24:27], v[120:123], v[192:195], v[60:63]
	v_mfma_f32_16x16x32_bf16 v[28:31], v[170:173], v[192:195], v[100:103]
	v_mfma_f32_16x16x32_bf16 v[60:63], v[120:123], v[200:203], v[104:107]
	v_mfma_f32_16x16x32_bf16 v[100:103], v[170:173], v[200:203], v[108:111]
	v_mfma_f32_16x16x32_bf16 v[16:19], v[120:123], v[208:211], v[16:19]
	v_mfma_f32_16x16x32_bf16 v[20:23], v[170:173], v[208:211], v[20:23]
	v_mfma_f32_16x16x32_bf16 v[8:11], v[124:127], v[184:187], v[8:11]
	v_mfma_f32_16x16x32_bf16 v[12:15], v[174:177], v[184:187], v[12:15]
	v_mfma_f32_16x16x32_bf16 v[24:27], v[124:127], v[196:199], v[24:27]
	v_mfma_f32_16x16x32_bf16 v[28:31], v[174:177], v[196:199], v[28:31]
	v_mfma_f32_16x16x32_bf16 v[60:63], v[124:127], v[204:207], v[60:63]
	v_mfma_f32_16x16x32_bf16 v[100:103], v[174:177], v[204:207], v[100:103]
	v_mfma_f32_16x16x32_bf16 v[16:19], v[124:127], v[212:215], v[16:19]
	v_mfma_f32_16x16x32_bf16 v[20:23], v[174:177], v[212:215], v[20:23]
	s_setprio 0
	s_barrier
	ds_read_b128 v[104:107], v145
	ds_read_b128 v[108:111], v145 offset:1024
	ds_read_b128 v[112:115], v145 offset:2048
	ds_read_b128 v[116:119], v145 offset:3072
	ds_read_b128 v[120:123], v146
	ds_read_b128 v[124:127], v146 offset:1024
	ds_read_b128 v[170:173], v146 offset:2048
	ds_read_b128 v[174:177], v146 offset:3072
	s_add_u32 s72, s90, 0x10180
	s_addc_u32 s73, s91, 0
	s_mov_b32 m0, s46
	v_lshl_add_u64 v[188:189], s[72:73], 0, v[128:129]
	ds_read_b128 v[180:183], v147
	ds_read_b128 v[184:187], v147 offset:1024
	ds_read_b128 v[192:195], v147 offset:2048
	ds_read_b128 v[196:199], v147 offset:3072
	ds_read_b128 v[200:203], v147 offset:4096
	ds_read_b128 v[204:207], v147 offset:5120
	ds_read_b128 v[208:211], v147 offset:6144
	ds_read_b128 v[212:215], v147 offset:7168
	global_load_lds_dwordx4 v[188:189], off
	v_lshl_add_u64 v[188:189], s[72:73], 0, v[130:131]
	s_mov_b32 m0, s29
	s_nop 0
	global_load_lds_dwordx4 v[188:189], off
	s_waitcnt vmcnt(8)
	s_waitcnt lgkmcnt(0)
	s_barrier
	s_setprio 1
	s_waitcnt lgkmcnt(0)
	v_mfma_f32_16x16x32_bf16 v[64:67], v[104:107], v[180:183], v[64:67]
	v_mfma_f32_16x16x32_bf16 v[68:71], v[112:115], v[180:183], v[68:71]
	v_mfma_f32_16x16x32_bf16 v[72:75], v[104:107], v[192:195], v[72:75]
	v_mfma_f32_16x16x32_bf16 v[76:79], v[112:115], v[192:195], v[76:79]
	v_mfma_f32_16x16x32_bf16 v[80:83], v[104:107], v[200:203], v[80:83]
	v_mfma_f32_16x16x32_bf16 v[84:87], v[112:115], v[200:203], v[84:87]
	v_mfma_f32_16x16x32_bf16 v[88:91], v[104:107], v[208:211], v[88:91]
	v_mfma_f32_16x16x32_bf16 v[64:67], v[108:111], v[184:187], v[64:67]
	v_mfma_f32_16x16x32_bf16 v[68:71], v[116:119], v[184:187], v[68:71]
	v_mfma_f32_16x16x32_bf16 v[72:75], v[108:111], v[196:199], v[72:75]
	v_mfma_f32_16x16x32_bf16 v[76:79], v[116:119], v[196:199], v[76:79]
	v_mfma_f32_16x16x32_bf16 v[80:83], v[108:111], v[204:207], v[80:83]
	v_mfma_f32_16x16x32_bf16 v[84:87], v[116:119], v[204:207], v[84:87]
	v_mfma_f32_16x16x32_bf16 v[216:219], v[108:111], v[212:215], v[88:91]
	v_mfma_f32_16x16x32_bf16 v[88:91], v[112:115], v[208:211], v[92:95]
	v_mfma_f32_16x16x32_bf16 v[220:223], v[116:119], v[212:215], v[88:91]
	v_mfma_f32_16x16x32_bf16 v[88:91], v[120:123], v[180:183], v[96:99]
	v_mfma_f32_16x16x32_bf16 v[32:35], v[170:173], v[180:183], v[32:35]
	v_mfma_f32_16x16x32_bf16 v[36:39], v[120:123], v[192:195], v[36:39]
	v_mfma_f32_16x16x32_bf16 v[40:43], v[170:173], v[192:195], v[40:43]
	v_mfma_f32_16x16x32_bf16 v[44:47], v[120:123], v[200:203], v[44:47]
	v_mfma_f32_16x16x32_bf16 v[48:51], v[170:173], v[200:203], v[48:51]
	v_mfma_f32_16x16x32_bf16 v[52:55], v[120:123], v[208:211], v[52:55]
	v_mfma_f32_16x16x32_bf16 v[56:59], v[170:173], v[208:211], v[56:59]
	v_mfma_f32_16x16x32_bf16 v[96:99], v[124:127], v[184:187], v[88:91]
	v_mfma_f32_16x16x32_bf16 v[32:35], v[174:177], v[184:187], v[32:35]
	v_mfma_f32_16x16x32_bf16 v[36:39], v[124:127], v[196:199], v[36:39]
	v_mfma_f32_16x16x32_bf16 v[40:43], v[174:177], v[196:199], v[40:43]
	v_mfma_f32_16x16x32_bf16 v[44:47], v[124:127], v[204:207], v[44:47]
	v_mfma_f32_16x16x32_bf16 v[48:51], v[174:177], v[204:207], v[48:51]
	v_mfma_f32_16x16x32_bf16 v[52:55], v[124:127], v[212:215], v[52:55]
	v_mfma_f32_16x16x32_bf16 v[56:59], v[174:177], v[212:215], v[56:59]
	s_setprio 0
	s_barrier
	s_mov_b32 m0, s44
	v_lshl_add_u64 v[188:189], vcc, 0, v[128:129]
	s_add_u32 s72, vcc_lo, 0x10000
	ds_read_b128 v[88:91], v147 offset:16384
	ds_read_b128 v[92:95], v147 offset:17408
	ds_read_b128 v[180:183], v147 offset:18432
	ds_read_b128 v[184:187], v147 offset:19456
	ds_read_b128 v[192:195], v147 offset:20480
	ds_read_b128 v[196:199], v147 offset:21504
	ds_read_b128 v[200:203], v147 offset:22528
	ds_read_b128 v[204:207], v147 offset:23552
	global_load_lds_dwordx4 v[188:189], off
	v_lshl_add_u64 v[190:191], vcc, 0, v[130:131]
	s_mov_b32 m0, s31
	s_addc_u32 s73, vcc_hi, 0
	global_load_lds_dwordx4 v[190:191], off
	v_lshl_add_u64 v[208:209], s[72:73], 0, v[128:129]
	s_mov_b32 m0, s42
	v_lshl_add_u64 v[134:135], s[82:83], 0, v[128:129]
	global_load_lds_dwordx4 v[208:209], off
	v_lshl_add_u64 v[208:209], s[72:73], 0, v[130:131]
	s_mov_b32 m0, s43
	v_lshl_add_u64 v[136:137], s[82:83], 0, v[130:131]
	global_load_lds_dwordx4 v[208:209], off
	s_mov_b32 m0, s21
	s_nop 0
	global_load_lds_dwordx4 v[134:135], off
	s_mov_b32 m0, s22
	s_nop 0
	global_load_lds_dwordx4 v[136:137], off
	s_waitcnt vmcnt(8)
	s_waitcnt lgkmcnt(0)
	s_barrier
	s_setprio 1
	s_waitcnt lgkmcnt(0)
	v_mfma_f32_16x16x32_bf16 v[0:3], v[104:107], v[200:203], v[0:3]
	v_mfma_f32_16x16x32_bf16 v[4:7], v[112:115], v[200:203], v[4:7]
	v_mfma_f32_16x16x32_bf16 v[138:141], v[104:107], v[88:91], v[138:141]
	v_mfma_f32_16x16x32_bf16 v[150:153], v[112:115], v[88:91], v[150:153]
	v_mfma_f32_16x16x32_bf16 v[154:157], v[104:107], v[180:183], v[154:157]
	v_mfma_f32_16x16x32_bf16 v[158:161], v[112:115], v[180:183], v[158:161]
	v_mfma_f32_16x16x32_bf16 v[162:165], v[104:107], v[192:195], v[162:165]
	v_mfma_f32_16x16x32_bf16 v[166:169], v[112:115], v[192:195], v[166:169]
	v_mfma_f32_16x16x32_bf16 v[0:3], v[108:111], v[204:207], v[0:3]
	v_mfma_f32_16x16x32_bf16 v[4:7], v[116:119], v[204:207], v[4:7]
	v_mfma_f32_16x16x32_bf16 v[138:141], v[108:111], v[92:95], v[138:141]
	v_mfma_f32_16x16x32_bf16 v[150:153], v[116:119], v[92:95], v[150:153]
	v_mfma_f32_16x16x32_bf16 v[154:157], v[108:111], v[184:187], v[154:157]
	v_mfma_f32_16x16x32_bf16 v[158:161], v[116:119], v[184:187], v[158:161]
	v_mfma_f32_16x16x32_bf16 v[162:165], v[108:111], v[196:199], v[162:165]
	v_mfma_f32_16x16x32_bf16 v[166:169], v[116:119], v[196:199], v[166:169]
	v_mfma_f32_16x16x32_bf16 v[8:11], v[120:123], v[88:91], v[8:11]
	v_mfma_f32_16x16x32_bf16 v[208:211], v[124:127], v[92:95], v[8:11]
	v_mfma_f32_16x16x32_bf16 v[8:11], v[170:173], v[88:91], v[12:15]
	v_mfma_f32_16x16x32_bf16 v[212:215], v[174:177], v[92:95], v[8:11]
	v_mfma_f32_16x16x32_bf16 v[8:11], v[120:123], v[180:183], v[24:27]
	v_mfma_f32_16x16x32_bf16 v[224:227], v[124:127], v[184:187], v[8:11]
	v_mfma_f32_16x16x32_bf16 v[8:11], v[170:173], v[180:183], v[28:31]
	v_mfma_f32_16x16x32_bf16 v[180:183], v[174:177], v[184:187], v[8:11]
	v_mfma_f32_16x16x32_bf16 v[8:11], v[120:123], v[192:195], v[60:63]
	v_mfma_f32_16x16x32_bf16 v[184:187], v[124:127], v[196:199], v[8:11]
	v_mfma_f32_16x16x32_bf16 v[8:11], v[170:173], v[192:195], v[100:103]
	v_mfma_f32_16x16x32_bf16 v[192:195], v[174:177], v[196:199], v[8:11]
	v_mfma_f32_16x16x32_bf16 v[8:11], v[120:123], v[200:203], v[16:19]
	v_mfma_f32_16x16x32_bf16 v[196:199], v[124:127], v[204:207], v[8:11]
	v_mfma_f32_16x16x32_bf16 v[8:11], v[170:173], v[200:203], v[20:23]
	v_mfma_f32_16x16x32_bf16 v[170:173], v[174:177], v[204:207], v[8:11]
	s_setprio 0
	s_barrier
	s_nop 4
	ds_read_b128 v[8:11], v132
	ds_read_b128 v[12:15], v132 offset:1024
	ds_read_b128 v[16:19], v132 offset:2048
	ds_read_b128 v[20:23], v132 offset:3072
	ds_read_b128 v[174:177], v149
	ds_read_b128 v[200:203], v149 offset:1024
	ds_read_b128 v[204:207], v149 offset:2048
	ds_read_b128 v[228:231], v149 offset:3072
	s_add_u32 s42, s82, 0x10000
	s_addc_u32 s43, s83, 0
	s_mov_b32 m0, s23
	v_lshl_add_u64 v[88:89], s[42:43], 0, v[128:129]
	ds_read_b128 v[24:27], v147 offset:32768
	ds_read_b128 v[28:31], v147 offset:33792
	ds_read_b128 v[60:63], v147 offset:34816
	ds_read_b128 v[232:235], v147 offset:35840
	ds_read_b128 v[236:239], v147 offset:36864
	ds_read_b128 v[240:243], v147 offset:37888
	ds_read_b128 v[244:247], v147 offset:38912
	ds_read_b128 v[248:251], v147 offset:39936
	global_load_lds_dwordx4 v[88:89], off
	v_lshl_add_u64 v[88:89], s[42:43], 0, v[130:131]
	s_mov_b32 m0, s24
	s_nop 0
	global_load_lds_dwordx4 v[88:89], off
	s_waitcnt vmcnt(8)
	s_waitcnt lgkmcnt(0)
	s_barrier
	s_setprio 1
	s_waitcnt lgkmcnt(0)
	v_mfma_f32_16x16x32_bf16 v[64:67], v[8:11], v[24:27], v[64:67]
	v_mfma_f32_16x16x32_bf16 v[124:127], v[12:15], v[28:31], v[64:67]
	v_mfma_f32_16x16x32_bf16 v[64:67], v[16:19], v[24:27], v[68:71]
	v_mfma_f32_16x16x32_bf16 v[120:123], v[20:23], v[28:31], v[64:67]
	v_mfma_f32_16x16x32_bf16 v[64:67], v[8:11], v[60:63], v[72:75]
	v_mfma_f32_16x16x32_bf16 v[108:111], v[12:15], v[232:235], v[64:67]
	v_mfma_f32_16x16x32_bf16 v[64:67], v[16:19], v[60:63], v[76:79]
	v_mfma_f32_16x16x32_bf16 v[104:107], v[20:23], v[232:235], v[64:67]
	v_mfma_f32_16x16x32_bf16 v[64:67], v[8:11], v[236:239], v[80:83]
	v_mfma_f32_16x16x32_bf16 v[92:95], v[12:15], v[240:243], v[64:67]
	v_mfma_f32_16x16x32_bf16 v[64:67], v[16:19], v[236:239], v[84:87]
	v_mfma_f32_16x16x32_bf16 v[88:91], v[20:23], v[240:243], v[64:67]
	v_mfma_f32_16x16x32_bf16 v[64:67], v[8:11], v[244:247], v[216:219]
	v_mfma_f32_16x16x32_bf16 v[76:79], v[12:15], v[248:251], v[64:67]
	v_mfma_f32_16x16x32_bf16 v[64:67], v[16:19], v[244:247], v[220:223]
	v_mfma_f32_16x16x32_bf16 v[72:75], v[20:23], v[248:251], v[64:67]
	v_mfma_f32_16x16x32_bf16 v[64:67], v[174:177], v[24:27], v[96:99]
	v_mfma_f32_16x16x32_bf16 v[24:27], v[204:207], v[24:27], v[32:35]
	v_mfma_f32_16x16x32_bf16 v[112:115], v[228:231], v[28:31], v[24:27]
	v_mfma_f32_16x16x32_bf16 v[24:27], v[174:177], v[60:63], v[36:39]
	v_mfma_f32_16x16x32_bf16 v[100:103], v[200:203], v[232:235], v[24:27]
	v_mfma_f32_16x16x32_bf16 v[24:27], v[204:207], v[60:63], v[40:43]
	v_mfma_f32_16x16x32_bf16 v[96:99], v[228:231], v[232:235], v[24:27]
	v_mfma_f32_16x16x32_bf16 v[24:27], v[174:177], v[236:239], v[44:47]
	v_mfma_f32_16x16x32_bf16 v[84:87], v[200:203], v[240:243], v[24:27]
	v_mfma_f32_16x16x32_bf16 v[24:27], v[204:207], v[236:239], v[48:51]
	v_mfma_f32_16x16x32_bf16 v[80:83], v[228:231], v[240:243], v[24:27]
	v_mfma_f32_16x16x32_bf16 v[24:27], v[174:177], v[244:247], v[52:55]
	v_mfma_f32_16x16x32_bf16 v[68:71], v[200:203], v[248:251], v[24:27]
	v_mfma_f32_16x16x32_bf16 v[24:27], v[204:207], v[244:247], v[56:59]
	v_mfma_f32_16x16x32_bf16 v[116:119], v[200:203], v[28:31], v[64:67]
	v_mfma_f32_16x16x32_bf16 v[64:67], v[228:231], v[248:251], v[24:27]
	s_setprio 0
	s_barrier
	s_mov_b32 m0, s71
	s_nop 2
	v_lshl_add_u64 v[24:25], v[188:189], 0, s[8:9]
	s_add_u32 s42, vcc_lo, 0x10080
	ds_read_b128 v[32:35], v147 offset:49152
	ds_read_b128 v[36:39], v147 offset:50176
	ds_read_b128 v[216:219], v147 offset:51200
	ds_read_b128 v[220:223], v147 offset:52224
	ds_read_b128 v[232:235], v147 offset:53248
	ds_read_b128 v[236:239], v147 offset:54272
	ds_read_b128 v[240:243], v147 offset:55296
	ds_read_b128 v[244:247], v147 offset:56320
	global_load_lds_dwordx4 v[24:25], off
	v_lshl_add_u64 v[24:25], v[190:191], 0, s[8:9]
	s_mov_b32 m0, s45
	s_addc_u32 s43, vcc_hi, 0
	global_load_lds_dwordx4 v[24:25], off
	v_lshl_add_u64 v[24:25], s[42:43], 0, v[128:129]
	s_mov_b32 m0, s47
	s_nop 0
	global_load_lds_dwordx4 v[24:25], off
	v_lshl_add_u64 v[24:25], s[42:43], 0, v[130:131]
	s_mov_b32 m0, s70
	s_nop 0
	global_load_lds_dwordx4 v[24:25], off
	v_lshl_add_u64 v[24:25], v[134:135], 0, s[8:9]
	s_mov_b32 m0, s25
	s_nop 0
	global_load_lds_dwordx4 v[24:25], off
	v_lshl_add_u64 v[24:25], v[136:137], 0, s[8:9]
	s_mov_b32 m0, s33
	s_nop 0
	global_load_lds_dwordx4 v[24:25], off
	s_waitcnt vmcnt(8)
	s_waitcnt lgkmcnt(0)
	s_barrier
	s_setprio 1
	s_waitcnt lgkmcnt(0)
	v_mfma_f32_16x16x32_bf16 v[24:27], v[8:11], v[32:35], v[138:141]
	v_mfma_f32_16x16x32_bf16 v[60:63], v[12:15], v[36:39], v[24:27]
	v_mfma_f32_16x16x32_bf16 v[24:27], v[16:19], v[32:35], v[150:153]
	v_mfma_f32_16x16x32_bf16 v[56:59], v[20:23], v[36:39], v[24:27]
	v_mfma_f32_16x16x32_bf16 v[24:27], v[8:11], v[216:219], v[154:157]
	v_mfma_f32_16x16x32_bf16 v[44:47], v[12:15], v[220:223], v[24:27]
	v_mfma_f32_16x16x32_bf16 v[24:27], v[16:19], v[216:219], v[158:161]
	v_mfma_f32_16x16x32_bf16 v[40:43], v[20:23], v[220:223], v[24:27]
	v_mfma_f32_16x16x32_bf16 v[24:27], v[8:11], v[232:235], v[162:165]
	v_mfma_f32_16x16x32_bf16 v[0:3], v[8:11], v[240:243], v[0:3]
	v_mfma_f32_16x16x32_bf16 v[28:31], v[12:15], v[236:239], v[24:27]
	v_mfma_f32_16x16x32_bf16 v[24:27], v[16:19], v[232:235], v[166:169]
	v_mfma_f32_16x16x32_bf16 v[12:15], v[12:15], v[244:247], v[0:3]
	v_mfma_f32_16x16x32_bf16 v[0:3], v[16:19], v[240:243], v[4:7]
	v_mfma_f32_16x16x32_bf16 v[24:27], v[20:23], v[236:239], v[24:27]
	v_mfma_f32_16x16x32_bf16 v[8:11], v[20:23], v[244:247], v[0:3]
	v_mfma_f32_16x16x32_bf16 v[0:3], v[174:177], v[32:35], v[208:211]
	v_mfma_f32_16x16x32_bf16 v[52:55], v[200:203], v[36:39], v[0:3]
	v_mfma_f32_16x16x32_bf16 v[0:3], v[204:207], v[32:35], v[212:215]
	v_mfma_f32_16x16x32_bf16 v[48:51], v[228:231], v[36:39], v[0:3]
	v_mfma_f32_16x16x32_bf16 v[0:3], v[174:177], v[216:219], v[224:227]
	v_mfma_f32_16x16x32_bf16 v[36:39], v[200:203], v[220:223], v[0:3]
	v_mfma_f32_16x16x32_bf16 v[0:3], v[204:207], v[216:219], v[180:183]
	v_mfma_f32_16x16x32_bf16 v[32:35], v[228:231], v[220:223], v[0:3]
	v_mfma_f32_16x16x32_bf16 v[0:3], v[174:177], v[232:235], v[184:187]
	v_mfma_f32_16x16x32_bf16 v[20:23], v[200:203], v[236:239], v[0:3]
	v_mfma_f32_16x16x32_bf16 v[0:3], v[204:207], v[232:235], v[192:195]
	v_mfma_f32_16x16x32_bf16 v[16:19], v[228:231], v[236:239], v[0:3]
	v_mfma_f32_16x16x32_bf16 v[0:3], v[174:177], v[240:243], v[196:199]
	v_mfma_f32_16x16x32_bf16 v[4:7], v[200:203], v[244:247], v[0:3]
	v_mfma_f32_16x16x32_bf16 v[0:3], v[204:207], v[240:243], v[170:173]
	v_mfma_f32_16x16x32_bf16 v[0:3], v[228:231], v[244:247], v[0:3]
	s_setprio 0
	s_barrier
	s_andn2_b64 vcc, exec, s[10:11]
	s_cbranch_vccnz .LBB0_431
	s_barrier

.LBB0_855:
	ds_read_b128 v[140:143], v147
	ds_read_b128 v[150:153], v147 offset:1024
	ds_read_b128 v[154:157], v147 offset:2048
	ds_read_b128 v[158:161], v147 offset:3072
	ds_read_b128 v[162:165], v148
	ds_read_b128 v[166:169], v148 offset:1024
	ds_read_b128 v[170:173], v148 offset:2048
	ds_read_b128 v[174:177], v148 offset:3072
	s_add_u32 s70, s48, 0x100
	s_addc_u32 s71, s49, 0
	s_cmp_eq_u32 s44, 28
	s_cselect_b32 s75, s15, s71
	s_cselect_b32 s74, s29, s70
	s_cselect_b32 s73, s13, s43
	s_cselect_b32 s72, s39, s42
	v_lshl_add_u64 v[188:189], s[48:49], 0, v[132:133]
	s_add_i32 m0, s21, 0xc000
	ds_read_b128 v[180:183], v149
	ds_read_b128 v[184:187], v149 offset:1024
	ds_read_b128 v[192:195], v149 offset:2048
	ds_read_b128 v[196:199], v149 offset:3072
	ds_read_b128 v[200:203], v149 offset:4096
	ds_read_b128 v[204:207], v149 offset:5120
	ds_read_b128 v[208:211], v149 offset:6144
	ds_read_b128 v[212:215], v149 offset:7168
	global_load_lds_dwordx4 v[188:189], off
	v_lshl_add_u64 v[188:189], s[48:49], 0, v[134:135]
	s_add_i32 m0, s21, 0xe000
	s_nop 0
	global_load_lds_dwordx4 v[188:189], off
	s_waitcnt vmcnt(8)
	s_waitcnt lgkmcnt(0)
	s_barrier
	s_setprio 1
	s_waitcnt lgkmcnt(0)
	v_mfma_f32_16x16x32_bf16 v[124:127], v[140:143], v[180:183], v[124:127]
	v_mfma_f32_16x16x32_bf16 v[120:123], v[154:157], v[180:183], v[120:123]
	v_mfma_f32_16x16x32_bf16 v[108:111], v[140:143], v[192:195], v[108:111]
	v_mfma_f32_16x16x32_bf16 v[104:107], v[154:157], v[192:195], v[104:107]
	v_mfma_f32_16x16x32_bf16 v[92:95], v[140:143], v[200:203], v[92:95]
	v_mfma_f32_16x16x32_bf16 v[88:91], v[154:157], v[200:203], v[88:91]
	v_mfma_f32_16x16x32_bf16 v[76:79], v[140:143], v[208:211], v[76:79]
	v_mfma_f32_16x16x32_bf16 v[72:75], v[154:157], v[208:211], v[72:75]
	v_mfma_f32_16x16x32_bf16 v[124:127], v[150:153], v[184:187], v[124:127]
	v_mfma_f32_16x16x32_bf16 v[120:123], v[158:161], v[184:187], v[120:123]
	v_mfma_f32_16x16x32_bf16 v[108:111], v[150:153], v[196:199], v[108:111]
	v_mfma_f32_16x16x32_bf16 v[104:107], v[158:161], v[196:199], v[104:107]
	v_mfma_f32_16x16x32_bf16 v[92:95], v[150:153], v[204:207], v[92:95]
	v_mfma_f32_16x16x32_bf16 v[88:91], v[158:161], v[204:207], v[88:91]
	v_mfma_f32_16x16x32_bf16 v[76:79], v[150:153], v[212:215], v[76:79]
	v_mfma_f32_16x16x32_bf16 v[72:75], v[158:161], v[212:215], v[72:75]
	v_mfma_f32_16x16x32_bf16 v[116:119], v[162:165], v[180:183], v[116:119]
	v_mfma_f32_16x16x32_bf16 v[112:115], v[170:173], v[180:183], v[112:115]
	v_mfma_f32_16x16x32_bf16 v[100:103], v[162:165], v[192:195], v[100:103]
	v_mfma_f32_16x16x32_bf16 v[96:99], v[170:173], v[192:195], v[96:99]
	v_mfma_f32_16x16x32_bf16 v[84:87], v[162:165], v[200:203], v[84:87]
	v_mfma_f32_16x16x32_bf16 v[80:83], v[170:173], v[200:203], v[80:83]
	v_mfma_f32_16x16x32_bf16 v[68:71], v[162:165], v[208:211], v[68:71]
	v_mfma_f32_16x16x32_bf16 v[64:67], v[170:173], v[208:211], v[64:67]
	v_mfma_f32_16x16x32_bf16 v[116:119], v[166:169], v[184:187], v[116:119]
	v_mfma_f32_16x16x32_bf16 v[112:115], v[174:177], v[184:187], v[112:115]
	v_mfma_f32_16x16x32_bf16 v[100:103], v[166:169], v[196:199], v[100:103]
	v_mfma_f32_16x16x32_bf16 v[96:99], v[174:177], v[196:199], v[96:99]
	v_mfma_f32_16x16x32_bf16 v[84:87], v[166:169], v[204:207], v[84:87]
	v_mfma_f32_16x16x32_bf16 v[80:83], v[174:177], v[204:207], v[80:83]
	v_mfma_f32_16x16x32_bf16 v[68:71], v[166:169], v[212:215], v[68:71]
	v_mfma_f32_16x16x32_bf16 v[64:67], v[174:177], v[212:215], v[64:67]
	s_setprio 0
	s_barrier
	s_add_i32 s45, s37, s20
	v_lshl_add_u64 v[188:189], s[72:73], 0, v[128:129]
	s_mov_b32 m0, s45
	ds_read_b128 v[180:183], v149 offset:16384
	ds_read_b128 v[184:187], v149 offset:17408
	ds_read_b128 v[192:195], v149 offset:18432
	ds_read_b128 v[196:199], v149 offset:19456
	ds_read_b128 v[200:203], v149 offset:20480
	ds_read_b128 v[204:207], v149 offset:21504
	ds_read_b128 v[208:211], v149 offset:22528
	ds_read_b128 v[212:215], v149 offset:23552
	global_load_lds_dwordx4 v[188:189], off
	s_add_i32 m0, s45, 0x2000
	s_add_u32 s46, s72, 0x80000
	v_lshl_add_u64 v[190:191], s[72:73], 0, v[130:131]
	s_addc_u32 s47, s73, 0
	s_add_i32 s45, s38, s20
	global_load_lds_dwordx4 v[190:191], off
	v_lshl_add_u64 v[216:217], s[46:47], 0, v[128:129]
	s_mov_b32 m0, s45
	v_lshl_add_u64 v[218:219], s[74:75], 0, v[130:131]
	global_load_lds_dwordx4 v[216:217], off
	v_lshl_add_u64 v[216:217], s[46:47], 0, v[130:131]
	s_add_i32 m0, s45, 0x2000
	s_nop 0
	global_load_lds_dwordx4 v[216:217], off
	v_lshl_add_u64 v[216:217], s[74:75], 0, v[128:129]
	s_mov_b32 m0, s21
	s_nop 0
	global_load_lds_dwordx4 v[216:217], off
	s_mov_b32 m0, s22
	s_nop 0
	global_load_lds_dwordx4 v[218:219], off
	s_waitcnt vmcnt(8)
	s_waitcnt lgkmcnt(0)
	s_barrier
	s_setprio 1
	s_waitcnt lgkmcnt(0)
	v_mfma_f32_16x16x32_bf16 v[60:63], v[140:143], v[180:183], v[60:63]
	v_mfma_f32_16x16x32_bf16 v[56:59], v[154:157], v[180:183], v[56:59]
	v_mfma_f32_16x16x32_bf16 v[44:47], v[140:143], v[192:195], v[44:47]
	v_mfma_f32_16x16x32_bf16 v[40:43], v[154:157], v[192:195], v[40:43]
	v_mfma_f32_16x16x32_bf16 v[28:31], v[140:143], v[200:203], v[28:31]
	v_mfma_f32_16x16x32_bf16 v[24:27], v[154:157], v[200:203], v[24:27]
	v_mfma_f32_16x16x32_bf16 v[12:15], v[140:143], v[208:211], v[12:15]
	v_mfma_f32_16x16x32_bf16 v[8:11], v[154:157], v[208:211], v[8:11]
	v_mfma_f32_16x16x32_bf16 v[60:63], v[150:153], v[184:187], v[60:63]
	v_mfma_f32_16x16x32_bf16 v[56:59], v[158:161], v[184:187], v[56:59]
	v_mfma_f32_16x16x32_bf16 v[44:47], v[150:153], v[196:199], v[44:47]
	v_mfma_f32_16x16x32_bf16 v[40:43], v[158:161], v[196:199], v[40:43]
	v_mfma_f32_16x16x32_bf16 v[28:31], v[150:153], v[204:207], v[28:31]
	v_mfma_f32_16x16x32_bf16 v[24:27], v[158:161], v[204:207], v[24:27]
	v_mfma_f32_16x16x32_bf16 v[12:15], v[150:153], v[212:215], v[12:15]
	v_mfma_f32_16x16x32_bf16 v[8:11], v[158:161], v[212:215], v[8:11]
	v_mfma_f32_16x16x32_bf16 v[52:55], v[162:165], v[180:183], v[52:55]
	v_mfma_f32_16x16x32_bf16 v[48:51], v[170:173], v[180:183], v[48:51]
	v_mfma_f32_16x16x32_bf16 v[36:39], v[162:165], v[192:195], v[36:39]
	v_mfma_f32_16x16x32_bf16 v[32:35], v[170:173], v[192:195], v[32:35]
	v_mfma_f32_16x16x32_bf16 v[20:23], v[162:165], v[200:203], v[20:23]
	v_mfma_f32_16x16x32_bf16 v[16:19], v[170:173], v[200:203], v[16:19]
	v_mfma_f32_16x16x32_bf16 v[4:7], v[162:165], v[208:211], v[4:7]
	v_mfma_f32_16x16x32_bf16 v[0:3], v[170:173], v[208:211], v[0:3]
	v_mfma_f32_16x16x32_bf16 v[52:55], v[166:169], v[184:187], v[52:55]
	v_mfma_f32_16x16x32_bf16 v[48:51], v[174:177], v[184:187], v[48:51]
	v_mfma_f32_16x16x32_bf16 v[36:39], v[166:169], v[196:199], v[36:39]
	v_mfma_f32_16x16x32_bf16 v[32:35], v[174:177], v[196:199], v[32:35]
	v_mfma_f32_16x16x32_bf16 v[20:23], v[166:169], v[204:207], v[20:23]
	v_mfma_f32_16x16x32_bf16 v[16:19], v[174:177], v[204:207], v[16:19]
	v_mfma_f32_16x16x32_bf16 v[4:7], v[166:169], v[212:215], v[4:7]
	v_mfma_f32_16x16x32_bf16 v[0:3], v[174:177], v[212:215], v[0:3]
	s_setprio 0
	s_barrier
	s_add_i32 s45, 0, 0x18000
	s_add_i32 s48, 0, 0x1c000
	v_add_u32_e32 v158, s45, v145
	v_add_u32_e32 v174, s48, v145
	ds_read_b128 v[140:143], v158
	ds_read_b128 v[150:153], v158 offset:1024
	ds_read_b128 v[154:157], v158 offset:2048
	ds_read_b128 v[158:161], v158 offset:3072
	ds_read_b128 v[162:165], v174
	ds_read_b128 v[166:169], v174 offset:1024
	ds_read_b128 v[170:173], v174 offset:2048
	ds_read_b128 v[174:177], v174 offset:3072
	s_add_u32 s46, s74, 0x80000
	s_addc_u32 s47, s75, 0
	s_mov_b32 m0, s23
	v_lshl_add_u64 v[220:221], s[46:47], 0, v[128:129]
	ds_read_b128 v[180:183], v149 offset:32768
	ds_read_b128 v[184:187], v149 offset:33792
	ds_read_b128 v[192:195], v149 offset:34816
	ds_read_b128 v[196:199], v149 offset:35840
	ds_read_b128 v[200:203], v149 offset:36864
	ds_read_b128 v[204:207], v149 offset:37888
	ds_read_b128 v[208:211], v149 offset:38912
	ds_read_b128 v[212:215], v149 offset:39936
	global_load_lds_dwordx4 v[220:221], off
	v_lshl_add_u64 v[220:221], s[46:47], 0, v[130:131]
	s_mov_b32 m0, s31
	s_nop 0
	global_load_lds_dwordx4 v[220:221], off
	s_waitcnt vmcnt(8)
	s_waitcnt lgkmcnt(0)
	s_barrier
	s_setprio 1
	s_waitcnt lgkmcnt(0)
	v_mfma_f32_16x16x32_bf16 v[124:127], v[140:143], v[180:183], v[124:127]
	v_mfma_f32_16x16x32_bf16 v[120:123], v[154:157], v[180:183], v[120:123]
	v_mfma_f32_16x16x32_bf16 v[108:111], v[140:143], v[192:195], v[108:111]
	v_mfma_f32_16x16x32_bf16 v[104:107], v[154:157], v[192:195], v[104:107]
	v_mfma_f32_16x16x32_bf16 v[92:95], v[140:143], v[200:203], v[92:95]
	v_mfma_f32_16x16x32_bf16 v[88:91], v[154:157], v[200:203], v[88:91]
	v_mfma_f32_16x16x32_bf16 v[76:79], v[140:143], v[208:211], v[76:79]
	v_mfma_f32_16x16x32_bf16 v[72:75], v[154:157], v[208:211], v[72:75]
	v_mfma_f32_16x16x32_bf16 v[124:127], v[150:153], v[184:187], v[124:127]
	v_mfma_f32_16x16x32_bf16 v[120:123], v[158:161], v[184:187], v[120:123]
	v_mfma_f32_16x16x32_bf16 v[108:111], v[150:153], v[196:199], v[108:111]
	v_mfma_f32_16x16x32_bf16 v[104:107], v[158:161], v[196:199], v[104:107]
	v_mfma_f32_16x16x32_bf16 v[92:95], v[150:153], v[204:207], v[92:95]
	v_mfma_f32_16x16x32_bf16 v[88:91], v[158:161], v[204:207], v[88:91]
	v_mfma_f32_16x16x32_bf16 v[76:79], v[150:153], v[212:215], v[76:79]
	v_mfma_f32_16x16x32_bf16 v[72:75], v[158:161], v[212:215], v[72:75]
	v_mfma_f32_16x16x32_bf16 v[116:119], v[162:165], v[180:183], v[116:119]
	v_mfma_f32_16x16x32_bf16 v[112:115], v[170:173], v[180:183], v[112:115]
	v_mfma_f32_16x16x32_bf16 v[100:103], v[162:165], v[192:195], v[100:103]
	v_mfma_f32_16x16x32_bf16 v[96:99], v[170:173], v[192:195], v[96:99]
	v_mfma_f32_16x16x32_bf16 v[84:87], v[162:165], v[200:203], v[84:87]
	v_mfma_f32_16x16x32_bf16 v[80:83], v[170:173], v[200:203], v[80:83]
	v_mfma_f32_16x16x32_bf16 v[68:71], v[162:165], v[208:211], v[68:71]
	v_mfma_f32_16x16x32_bf16 v[64:67], v[170:173], v[208:211], v[64:67]
	v_mfma_f32_16x16x32_bf16 v[116:119], v[166:169], v[184:187], v[116:119]
	v_mfma_f32_16x16x32_bf16 v[112:115], v[174:177], v[184:187], v[112:115]
	v_mfma_f32_16x16x32_bf16 v[100:103], v[166:169], v[196:199], v[100:103]
	v_mfma_f32_16x16x32_bf16 v[96:99], v[174:177], v[196:199], v[96:99]
	v_mfma_f32_16x16x32_bf16 v[84:87], v[166:169], v[204:207], v[84:87]
	v_mfma_f32_16x16x32_bf16 v[80:83], v[174:177], v[204:207], v[80:83]
	v_mfma_f32_16x16x32_bf16 v[68:71], v[166:169], v[212:215], v[68:71]
	v_mfma_f32_16x16x32_bf16 v[64:67], v[174:177], v[212:215], v[64:67]
	s_setprio 0
	s_barrier
	s_add_i32 s45, s45, s20
	v_lshl_add_u64 v[188:189], v[188:189], 0, s[8:9]
	s_mov_b32 m0, s45
	ds_read_b128 v[180:183], v149 offset:49152
	ds_read_b128 v[184:187], v149 offset:50176
	ds_read_b128 v[192:195], v149 offset:51200
	ds_read_b128 v[196:199], v149 offset:52224
	ds_read_b128 v[200:203], v149 offset:53248
	ds_read_b128 v[204:207], v149 offset:54272
	ds_read_b128 v[208:211], v149 offset:55296
	ds_read_b128 v[212:215], v149 offset:56320
	global_load_lds_dwordx4 v[188:189], off
	s_add_i32 m0, s45, 0x2000
	s_add_u32 s46, s72, 0x80080
	v_lshl_add_u64 v[188:189], v[190:191], 0, s[8:9]
	s_addc_u32 s47, s73, 0
	s_add_i32 s45, s48, s20
	global_load_lds_dwordx4 v[188:189], off
	v_lshl_add_u64 v[188:189], s[46:47], 0, v[128:129]
	s_mov_b32 m0, s45
	s_nop 0
	global_load_lds_dwordx4 v[188:189], off
	v_lshl_add_u64 v[188:189], s[46:47], 0, v[130:131]
	s_add_i32 m0, s45, 0x2000
	s_nop 0
	global_load_lds_dwordx4 v[188:189], off
	v_lshl_add_u64 v[188:189], v[216:217], 0, s[8:9]
	s_mov_b32 m0, s35
	s_nop 0
	global_load_lds_dwordx4 v[188:189], off
	v_lshl_add_u64 v[188:189], v[218:219], 0, s[8:9]
	s_mov_b32 m0, s36
	s_nop 0
	global_load_lds_dwordx4 v[188:189], off
	s_waitcnt vmcnt(8)
	s_waitcnt lgkmcnt(0)
	s_barrier
	s_setprio 1
	s_waitcnt lgkmcnt(0)
	v_mfma_f32_16x16x32_bf16 v[60:63], v[140:143], v[180:183], v[60:63]
	v_mfma_f32_16x16x32_bf16 v[56:59], v[154:157], v[180:183], v[56:59]
	v_mfma_f32_16x16x32_bf16 v[44:47], v[140:143], v[192:195], v[44:47]
	v_mfma_f32_16x16x32_bf16 v[40:43], v[154:157], v[192:195], v[40:43]
	v_mfma_f32_16x16x32_bf16 v[28:31], v[140:143], v[200:203], v[28:31]
	v_mfma_f32_16x16x32_bf16 v[24:27], v[154:157], v[200:203], v[24:27]
	v_mfma_f32_16x16x32_bf16 v[12:15], v[140:143], v[208:211], v[12:15]
	v_mfma_f32_16x16x32_bf16 v[8:11], v[154:157], v[208:211], v[8:11]
	v_mfma_f32_16x16x32_bf16 v[60:63], v[150:153], v[184:187], v[60:63]
	v_mfma_f32_16x16x32_bf16 v[56:59], v[158:161], v[184:187], v[56:59]
	v_mfma_f32_16x16x32_bf16 v[44:47], v[150:153], v[196:199], v[44:47]
	v_mfma_f32_16x16x32_bf16 v[40:43], v[158:161], v[196:199], v[40:43]
	v_mfma_f32_16x16x32_bf16 v[28:31], v[150:153], v[204:207], v[28:31]
	v_mfma_f32_16x16x32_bf16 v[24:27], v[158:161], v[204:207], v[24:27]
	v_mfma_f32_16x16x32_bf16 v[12:15], v[150:153], v[212:215], v[12:15]
	v_mfma_f32_16x16x32_bf16 v[8:11], v[158:161], v[212:215], v[8:11]
	v_mfma_f32_16x16x32_bf16 v[52:55], v[162:165], v[180:183], v[52:55]
	v_mfma_f32_16x16x32_bf16 v[48:51], v[170:173], v[180:183], v[48:51]
	v_mfma_f32_16x16x32_bf16 v[36:39], v[162:165], v[192:195], v[36:39]
	v_mfma_f32_16x16x32_bf16 v[32:35], v[170:173], v[192:195], v[32:35]
	v_mfma_f32_16x16x32_bf16 v[20:23], v[162:165], v[200:203], v[20:23]
	v_mfma_f32_16x16x32_bf16 v[16:19], v[170:173], v[200:203], v[16:19]
	v_mfma_f32_16x16x32_bf16 v[4:7], v[162:165], v[208:211], v[4:7]
	v_mfma_f32_16x16x32_bf16 v[0:3], v[170:173], v[208:211], v[0:3]
	v_mfma_f32_16x16x32_bf16 v[52:55], v[166:169], v[184:187], v[52:55]
	v_mfma_f32_16x16x32_bf16 v[48:51], v[174:177], v[184:187], v[48:51]
	v_mfma_f32_16x16x32_bf16 v[36:39], v[166:169], v[196:199], v[36:39]
	v_mfma_f32_16x16x32_bf16 v[32:35], v[174:177], v[196:199], v[32:35]
	v_mfma_f32_16x16x32_bf16 v[20:23], v[166:169], v[204:207], v[20:23]
	v_mfma_f32_16x16x32_bf16 v[16:19], v[174:177], v[204:207], v[16:19]
	v_mfma_f32_16x16x32_bf16 v[4:7], v[166:169], v[212:215], v[4:7]
	v_mfma_f32_16x16x32_bf16 v[0:3], v[174:177], v[212:215], v[0:3]
	s_setprio 0
	s_barrier
	s_add_i32 s44, s44, 2
	s_add_u32 s42, s42, 0x100
	s_addc_u32 s43, s43, 0
	s_cmp_gt_u32 s44, 29
	s_mov_b64 s[48:49], s[70:71]
	s_cbranch_scc0 .LBB0_855
	s_and_b64 vcc, exec, s[10:11]
	s_cbranch_vccz .LBB0_858
	s_barrier

.LBB0_953:
	ds_read_b128 v[144:147], v151
	ds_read_b128 v[156:159], v151 offset:1024
	ds_read_b128 v[160:163], v151 offset:2048
	ds_read_b128 v[164:167], v151 offset:3072
	ds_read_b128 v[168:171], v152
	ds_read_b128 v[172:175], v152 offset:1024
	ds_read_b128 v[180:183], v152 offset:2048
	ds_read_b128 v[184:187], v152 offset:3072
	s_add_u32 s30, s28, 0xfff80080
	s_addc_u32 s31, s29, -1
	s_cmp_eq_u32 s71, 28
	s_cselect_b32 s47, s15, s31
	s_cselect_b32 s46, s45, s30
	s_cselect_b32 s31, s13, s70
	s_cselect_b32 s30, s48, s49
	v_lshl_add_u64 v[176:177], s[28:29], 0, v[136:137]
	s_add_i32 m0, s22, 0xc000
	ds_read_b128 v[192:195], v153
	ds_read_b128 v[196:199], v153 offset:1024
	ds_read_b128 v[200:203], v153 offset:2048
	ds_read_b128 v[204:207], v153 offset:3072
	ds_read_b128 v[208:211], v153 offset:4096
	ds_read_b128 v[212:215], v153 offset:5120
	ds_read_b128 v[216:219], v153 offset:6144
	ds_read_b128 v[220:223], v153 offset:7168
	global_load_lds_dwordx4 v[176:177], off
	v_lshl_add_u64 v[176:177], s[28:29], 0, v[138:139]
	s_add_i32 m0, s22, 0xe000
	s_nop 0
	global_load_lds_dwordx4 v[176:177], off
	s_waitcnt vmcnt(8)
	s_waitcnt lgkmcnt(0)
	s_barrier
	s_setprio 1
	s_waitcnt lgkmcnt(0)
	v_mfma_f32_16x16x32_bf16 v[116:119], v[144:147], v[192:195], v[116:119]
	v_mfma_f32_16x16x32_bf16 v[112:115], v[160:163], v[192:195], v[112:115]
	v_mfma_f32_16x16x32_bf16 v[100:103], v[144:147], v[200:203], v[100:103]
	v_mfma_f32_16x16x32_bf16 v[96:99], v[160:163], v[200:203], v[96:99]
	v_mfma_f32_16x16x32_bf16 v[84:87], v[144:147], v[208:211], v[84:87]
	v_mfma_f32_16x16x32_bf16 v[80:83], v[160:163], v[208:211], v[80:83]
	v_mfma_f32_16x16x32_bf16 v[72:75], v[144:147], v[216:219], v[72:75]
	v_mfma_f32_16x16x32_bf16 v[64:67], v[160:163], v[216:219], v[64:67]
	v_mfma_f32_16x16x32_bf16 v[116:119], v[156:159], v[196:199], v[116:119]
	v_mfma_f32_16x16x32_bf16 v[112:115], v[164:167], v[196:199], v[112:115]
	v_mfma_f32_16x16x32_bf16 v[100:103], v[156:159], v[204:207], v[100:103]
	v_mfma_f32_16x16x32_bf16 v[96:99], v[164:167], v[204:207], v[96:99]
	v_mfma_f32_16x16x32_bf16 v[84:87], v[156:159], v[212:215], v[84:87]
	v_mfma_f32_16x16x32_bf16 v[80:83], v[164:167], v[212:215], v[80:83]
	v_mfma_f32_16x16x32_bf16 v[72:75], v[156:159], v[220:223], v[72:75]
	v_mfma_f32_16x16x32_bf16 v[64:67], v[164:167], v[220:223], v[64:67]
	v_mfma_f32_16x16x32_bf16 v[124:127], v[168:171], v[192:195], v[124:127]
	v_mfma_f32_16x16x32_bf16 v[120:123], v[180:183], v[192:195], v[120:123]
	v_mfma_f32_16x16x32_bf16 v[108:111], v[168:171], v[200:203], v[108:111]
	v_mfma_f32_16x16x32_bf16 v[104:107], v[180:183], v[200:203], v[104:107]
	v_mfma_f32_16x16x32_bf16 v[92:95], v[168:171], v[208:211], v[92:95]
	v_mfma_f32_16x16x32_bf16 v[88:91], v[180:183], v[208:211], v[88:91]
	v_mfma_f32_16x16x32_bf16 v[76:79], v[168:171], v[216:219], v[76:79]
	v_mfma_f32_16x16x32_bf16 v[68:71], v[180:183], v[216:219], v[68:71]
	v_mfma_f32_16x16x32_bf16 v[124:127], v[172:175], v[196:199], v[124:127]
	v_mfma_f32_16x16x32_bf16 v[120:123], v[184:187], v[196:199], v[120:123]
	v_mfma_f32_16x16x32_bf16 v[108:111], v[172:175], v[204:207], v[108:111]
	v_mfma_f32_16x16x32_bf16 v[104:107], v[184:187], v[204:207], v[104:107]
	v_mfma_f32_16x16x32_bf16 v[92:95], v[172:175], v[212:215], v[92:95]
	v_mfma_f32_16x16x32_bf16 v[88:91], v[184:187], v[212:215], v[88:91]
	v_mfma_f32_16x16x32_bf16 v[76:79], v[172:175], v[220:223], v[76:79]
	v_mfma_f32_16x16x32_bf16 v[68:71], v[184:187], v[220:223], v[68:71]
	s_setprio 0
	s_barrier
	s_add_i32 s72, s39, s20
	v_lshl_add_u64 v[176:177], s[30:31], 0, v[132:133]
	s_mov_b32 m0, s72
	ds_read_b128 v[192:195], v153 offset:16384
	ds_read_b128 v[196:199], v153 offset:17408
	ds_read_b128 v[200:203], v153 offset:18432
	ds_read_b128 v[204:207], v153 offset:19456
	ds_read_b128 v[208:211], v153 offset:20480
	ds_read_b128 v[212:215], v153 offset:21504
	ds_read_b128 v[216:219], v153 offset:22528
	ds_read_b128 v[220:223], v153 offset:23552
	global_load_lds_dwordx4 v[176:177], off
	s_add_i32 m0, s72, 0x2000
	s_add_u32 s72, s30, 0x80000
	v_lshl_add_u64 v[188:189], s[30:31], 0, v[128:129]
	s_addc_u32 s73, s31, 0
	s_add_i32 s74, s42, s20
	global_load_lds_dwordx4 v[188:189], off
	v_lshl_add_u64 v[190:191], s[72:73], 0, v[132:133]
	s_mov_b32 m0, s74
	v_lshl_add_u64 v[224:225], s[46:47], 0, v[130:131]
	global_load_lds_dwordx4 v[190:191], off
	v_lshl_add_u64 v[190:191], s[72:73], 0, v[128:129]
	s_add_i32 m0, s74, 0x2000
	s_nop 0
	global_load_lds_dwordx4 v[190:191], off
	v_lshl_add_u64 v[190:191], s[46:47], 0, v[134:135]
	s_mov_b32 m0, s22
	s_nop 0
	global_load_lds_dwordx4 v[190:191], off
	s_mov_b32 m0, s23
	s_nop 0
	global_load_lds_dwordx4 v[224:225], off
	s_waitcnt vmcnt(8)
	s_waitcnt lgkmcnt(0)
	s_barrier
	s_setprio 1
	s_waitcnt lgkmcnt(0)
	v_mfma_f32_16x16x32_bf16 v[56:59], v[144:147], v[192:195], v[56:59]
	v_mfma_f32_16x16x32_bf16 v[48:51], v[160:163], v[192:195], v[48:51]
	v_mfma_f32_16x16x32_bf16 v[40:43], v[144:147], v[200:203], v[40:43]
	v_mfma_f32_16x16x32_bf16 v[32:35], v[160:163], v[200:203], v[32:35]
	v_mfma_f32_16x16x32_bf16 v[24:27], v[144:147], v[208:211], v[24:27]
	v_mfma_f32_16x16x32_bf16 v[16:19], v[160:163], v[208:211], v[16:19]
	v_mfma_f32_16x16x32_bf16 v[8:11], v[144:147], v[216:219], v[8:11]
	v_mfma_f32_16x16x32_bf16 v[0:3], v[160:163], v[216:219], v[0:3]
	v_mfma_f32_16x16x32_bf16 v[56:59], v[156:159], v[196:199], v[56:59]
	v_mfma_f32_16x16x32_bf16 v[48:51], v[164:167], v[196:199], v[48:51]
	v_mfma_f32_16x16x32_bf16 v[40:43], v[156:159], v[204:207], v[40:43]
	v_mfma_f32_16x16x32_bf16 v[32:35], v[164:167], v[204:207], v[32:35]
	v_mfma_f32_16x16x32_bf16 v[24:27], v[156:159], v[212:215], v[24:27]
	v_mfma_f32_16x16x32_bf16 v[16:19], v[164:167], v[212:215], v[16:19]
	v_mfma_f32_16x16x32_bf16 v[8:11], v[156:159], v[220:223], v[8:11]
	v_mfma_f32_16x16x32_bf16 v[0:3], v[164:167], v[220:223], v[0:3]
	v_mfma_f32_16x16x32_bf16 v[60:63], v[168:171], v[192:195], v[60:63]
	v_mfma_f32_16x16x32_bf16 v[52:55], v[180:183], v[192:195], v[52:55]
	v_mfma_f32_16x16x32_bf16 v[44:47], v[168:171], v[200:203], v[44:47]
	v_mfma_f32_16x16x32_bf16 v[36:39], v[180:183], v[200:203], v[36:39]
	v_mfma_f32_16x16x32_bf16 v[28:31], v[168:171], v[208:211], v[28:31]
	v_mfma_f32_16x16x32_bf16 v[20:23], v[180:183], v[208:211], v[20:23]
	v_mfma_f32_16x16x32_bf16 v[12:15], v[168:171], v[216:219], v[12:15]
	v_mfma_f32_16x16x32_bf16 v[4:7], v[180:183], v[216:219], v[4:7]
	v_mfma_f32_16x16x32_bf16 v[60:63], v[172:175], v[196:199], v[60:63]
	v_mfma_f32_16x16x32_bf16 v[52:55], v[184:187], v[196:199], v[52:55]
	v_mfma_f32_16x16x32_bf16 v[44:47], v[172:175], v[204:207], v[44:47]
	v_mfma_f32_16x16x32_bf16 v[36:39], v[184:187], v[204:207], v[36:39]
	v_mfma_f32_16x16x32_bf16 v[28:31], v[172:175], v[212:215], v[28:31]
	v_mfma_f32_16x16x32_bf16 v[20:23], v[184:187], v[212:215], v[20:23]
	v_mfma_f32_16x16x32_bf16 v[12:15], v[172:175], v[220:223], v[12:15]
	v_mfma_f32_16x16x32_bf16 v[4:7], v[184:187], v[220:223], v[4:7]
	s_setprio 0
	s_barrier
	s_add_i32 s72, 0, 0x18000
	v_add_u32_e32 v155, s72, v149
	s_add_i32 s73, 0, 0x1c000
	ds_read_b128 v[144:147], v155
	ds_read_b128 v[156:159], v155 offset:1024
	ds_read_b128 v[160:163], v155 offset:2048
	ds_read_b128 v[164:167], v155 offset:3072
	v_add_u32_e32 v155, s73, v149
	ds_read_b128 v[168:171], v155
	ds_read_b128 v[172:175], v155 offset:1024
	ds_read_b128 v[180:183], v155 offset:2048
	ds_read_b128 v[184:187], v155 offset:3072
	s_add_u32 s46, s46, 0x80000
	s_addc_u32 s47, s47, 0
	s_mov_b32 m0, s33
	v_lshl_add_u64 v[226:227], s[46:47], 0, v[134:135]
	ds_read_b128 v[192:195], v153 offset:32768
	ds_read_b128 v[196:199], v153 offset:33792
	ds_read_b128 v[200:203], v153 offset:34816
	ds_read_b128 v[204:207], v153 offset:35840
	ds_read_b128 v[208:211], v153 offset:36864
	ds_read_b128 v[212:215], v153 offset:37888
	ds_read_b128 v[216:219], v153 offset:38912
	ds_read_b128 v[220:223], v153 offset:39936
	global_load_lds_dwordx4 v[226:227], off
	v_lshl_add_u64 v[226:227], s[46:47], 0, v[130:131]
	s_mov_b32 m0, s35
	s_nop 0
	global_load_lds_dwordx4 v[226:227], off
	s_waitcnt vmcnt(8)
	s_waitcnt lgkmcnt(0)
	s_barrier
	s_setprio 1
	s_waitcnt lgkmcnt(0)
	v_mfma_f32_16x16x32_bf16 v[116:119], v[144:147], v[192:195], v[116:119]
	v_mfma_f32_16x16x32_bf16 v[112:115], v[160:163], v[192:195], v[112:115]
	v_mfma_f32_16x16x32_bf16 v[100:103], v[144:147], v[200:203], v[100:103]
	v_mfma_f32_16x16x32_bf16 v[96:99], v[160:163], v[200:203], v[96:99]
	v_mfma_f32_16x16x32_bf16 v[84:87], v[144:147], v[208:211], v[84:87]
	v_mfma_f32_16x16x32_bf16 v[80:83], v[160:163], v[208:211], v[80:83]
	v_mfma_f32_16x16x32_bf16 v[72:75], v[144:147], v[216:219], v[72:75]
	v_mfma_f32_16x16x32_bf16 v[64:67], v[160:163], v[216:219], v[64:67]
	v_mfma_f32_16x16x32_bf16 v[116:119], v[156:159], v[196:199], v[116:119]
	v_mfma_f32_16x16x32_bf16 v[112:115], v[164:167], v[196:199], v[112:115]
	v_mfma_f32_16x16x32_bf16 v[100:103], v[156:159], v[204:207], v[100:103]
	v_mfma_f32_16x16x32_bf16 v[96:99], v[164:167], v[204:207], v[96:99]
	v_mfma_f32_16x16x32_bf16 v[84:87], v[156:159], v[212:215], v[84:87]
	v_mfma_f32_16x16x32_bf16 v[80:83], v[164:167], v[212:215], v[80:83]
	v_mfma_f32_16x16x32_bf16 v[72:75], v[156:159], v[220:223], v[72:75]
	v_mfma_f32_16x16x32_bf16 v[64:67], v[164:167], v[220:223], v[64:67]
	v_mfma_f32_16x16x32_bf16 v[124:127], v[168:171], v[192:195], v[124:127]
	v_mfma_f32_16x16x32_bf16 v[120:123], v[180:183], v[192:195], v[120:123]
	v_mfma_f32_16x16x32_bf16 v[108:111], v[168:171], v[200:203], v[108:111]
	v_mfma_f32_16x16x32_bf16 v[104:107], v[180:183], v[200:203], v[104:107]
	v_mfma_f32_16x16x32_bf16 v[92:95], v[168:171], v[208:211], v[92:95]
	v_mfma_f32_16x16x32_bf16 v[88:91], v[180:183], v[208:211], v[88:91]
	v_mfma_f32_16x16x32_bf16 v[76:79], v[168:171], v[216:219], v[76:79]
	v_mfma_f32_16x16x32_bf16 v[68:71], v[180:183], v[216:219], v[68:71]
	v_mfma_f32_16x16x32_bf16 v[124:127], v[172:175], v[196:199], v[124:127]
	v_mfma_f32_16x16x32_bf16 v[120:123], v[184:187], v[196:199], v[120:123]
	v_mfma_f32_16x16x32_bf16 v[108:111], v[172:175], v[204:207], v[108:111]
	v_mfma_f32_16x16x32_bf16 v[104:107], v[184:187], v[204:207], v[104:107]
	v_mfma_f32_16x16x32_bf16 v[92:95], v[172:175], v[212:215], v[92:95]
	v_mfma_f32_16x16x32_bf16 v[88:91], v[184:187], v[212:215], v[88:91]
	v_mfma_f32_16x16x32_bf16 v[76:79], v[172:175], v[220:223], v[76:79]
	v_mfma_f32_16x16x32_bf16 v[68:71], v[184:187], v[220:223], v[68:71]
	s_setprio 0
	s_barrier
	s_add_i32 s46, s72, s20
	v_lshl_add_u64 v[176:177], v[176:177], 0, s[8:9]
	s_mov_b32 m0, s46
	ds_read_b128 v[192:195], v153 offset:49152
	ds_read_b128 v[196:199], v153 offset:50176
	ds_read_b128 v[200:203], v153 offset:51200
	ds_read_b128 v[204:207], v153 offset:52224
	ds_read_b128 v[208:211], v153 offset:53248
	ds_read_b128 v[212:215], v153 offset:54272
	ds_read_b128 v[216:219], v153 offset:55296
	ds_read_b128 v[220:223], v153 offset:56320
	global_load_lds_dwordx4 v[176:177], off
	s_add_i32 m0, s46, 0x2000
	s_add_u32 s30, s30, 0x80080
	v_lshl_add_u64 v[176:177], v[188:189], 0, s[8:9]
	s_addc_u32 s31, s31, 0
	s_add_i32 s46, s73, s20
	global_load_lds_dwordx4 v[176:177], off
	v_lshl_add_u64 v[176:177], s[30:31], 0, v[132:133]
	s_mov_b32 m0, s46
	s_nop 0
	global_load_lds_dwordx4 v[176:177], off
	v_lshl_add_u64 v[176:177], s[30:31], 0, v[128:129]
	s_add_i32 m0, s46, 0x2000
	s_nop 0
	global_load_lds_dwordx4 v[176:177], off
	v_lshl_add_u64 v[176:177], v[190:191], 0, s[8:9]
	s_mov_b32 m0, s37
	s_nop 0
	global_load_lds_dwordx4 v[176:177], off
	v_lshl_add_u64 v[176:177], v[224:225], 0, s[8:9]
	s_mov_b32 m0, s38
	s_nop 0
	global_load_lds_dwordx4 v[176:177], off
	s_waitcnt vmcnt(8)
	s_waitcnt lgkmcnt(0)
	s_barrier
	s_setprio 1
	s_waitcnt lgkmcnt(0)
	v_mfma_f32_16x16x32_bf16 v[56:59], v[144:147], v[192:195], v[56:59]
	v_mfma_f32_16x16x32_bf16 v[48:51], v[160:163], v[192:195], v[48:51]
	v_mfma_f32_16x16x32_bf16 v[40:43], v[144:147], v[200:203], v[40:43]
	v_mfma_f32_16x16x32_bf16 v[32:35], v[160:163], v[200:203], v[32:35]
	v_mfma_f32_16x16x32_bf16 v[24:27], v[144:147], v[208:211], v[24:27]
	v_mfma_f32_16x16x32_bf16 v[16:19], v[160:163], v[208:211], v[16:19]
	v_mfma_f32_16x16x32_bf16 v[8:11], v[144:147], v[216:219], v[8:11]
	v_mfma_f32_16x16x32_bf16 v[0:3], v[160:163], v[216:219], v[0:3]
	v_mfma_f32_16x16x32_bf16 v[56:59], v[156:159], v[196:199], v[56:59]
	v_mfma_f32_16x16x32_bf16 v[48:51], v[164:167], v[196:199], v[48:51]
	v_mfma_f32_16x16x32_bf16 v[40:43], v[156:159], v[204:207], v[40:43]
	v_mfma_f32_16x16x32_bf16 v[32:35], v[164:167], v[204:207], v[32:35]
	v_mfma_f32_16x16x32_bf16 v[24:27], v[156:159], v[212:215], v[24:27]
	v_mfma_f32_16x16x32_bf16 v[16:19], v[164:167], v[212:215], v[16:19]
	v_mfma_f32_16x16x32_bf16 v[8:11], v[156:159], v[220:223], v[8:11]
	v_mfma_f32_16x16x32_bf16 v[0:3], v[164:167], v[220:223], v[0:3]
	v_mfma_f32_16x16x32_bf16 v[60:63], v[168:171], v[192:195], v[60:63]
	v_mfma_f32_16x16x32_bf16 v[52:55], v[180:183], v[192:195], v[52:55]
	v_mfma_f32_16x16x32_bf16 v[44:47], v[168:171], v[200:203], v[44:47]
	v_mfma_f32_16x16x32_bf16 v[36:39], v[180:183], v[200:203], v[36:39]
	v_mfma_f32_16x16x32_bf16 v[28:31], v[168:171], v[208:211], v[28:31]
	v_mfma_f32_16x16x32_bf16 v[20:23], v[180:183], v[208:211], v[20:23]
	v_mfma_f32_16x16x32_bf16 v[12:15], v[168:171], v[216:219], v[12:15]
	v_mfma_f32_16x16x32_bf16 v[4:7], v[180:183], v[216:219], v[4:7]
	v_mfma_f32_16x16x32_bf16 v[60:63], v[172:175], v[196:199], v[60:63]
	v_mfma_f32_16x16x32_bf16 v[52:55], v[184:187], v[196:199], v[52:55]
	v_mfma_f32_16x16x32_bf16 v[44:47], v[172:175], v[204:207], v[44:47]
	v_mfma_f32_16x16x32_bf16 v[36:39], v[184:187], v[204:207], v[36:39]
	v_mfma_f32_16x16x32_bf16 v[28:31], v[172:175], v[212:215], v[28:31]
	v_mfma_f32_16x16x32_bf16 v[20:23], v[184:187], v[212:215], v[20:23]
	v_mfma_f32_16x16x32_bf16 v[12:15], v[172:175], v[220:223], v[12:15]
	v_mfma_f32_16x16x32_bf16 v[4:7], v[184:187], v[220:223], v[4:7]
	s_setprio 0
	s_barrier
	s_add_i32 s71, s71, 2
	s_add_u32 s28, s28, 0x100
	s_addc_u32 s29, s29, 0
	s_add_u32 s49, s49, 0x100
	s_addc_u32 s70, s70, 0
	s_cmp_gt_u32 s71, 29
	s_cbranch_scc0 .LBB0_953
	s_and_b64 vcc, exec, s[10:11]
	s_cbranch_vccz .LBB0_956
	s_barrier

.LBB0_1040:
	ds_read_b128 v[140:143], v171
	ds_read_b128 v[144:147], v171 offset:1024
	ds_read_b128 v[148:151], v171 offset:2048
	ds_read_b128 v[152:155], v171 offset:3072
	ds_read_b128 v[156:159], v172
	ds_read_b128 v[160:163], v172 offset:1024
	ds_read_b128 v[164:167], v172 offset:2048
	ds_read_b128 v[180:183], v172 offset:3072
	s_add_u32 s22, s24, 0x100
	s_addc_u32 s23, s25, 0
	s_cmpk_eq_i32 s49, 0x54
	s_cselect_b32 s29, s7, s23
	s_cselect_b32 s28, s6, s22
	s_cselect_b32 s27, s15, s48
	s_cselect_b32 s26, s14, s47
	v_lshl_add_u64 v[176:177], s[24:25], 0, v[132:133]
	s_add_i32 m0, s21, 0xc000
	ds_read_b128 v[184:187], v173
	ds_read_b128 v[188:191], v173 offset:1024
	ds_read_b128 v[192:195], v173 offset:2048
	ds_read_b128 v[196:199], v173 offset:3072
	ds_read_b128 v[200:203], v173 offset:4096
	ds_read_b128 v[204:207], v173 offset:5120
	ds_read_b128 v[208:211], v173 offset:6144
	ds_read_b128 v[212:215], v173 offset:7168
	global_load_lds_dwordx4 v[176:177], off
	v_lshl_add_u64 v[176:177], s[24:25], 0, v[134:135]
	s_add_i32 m0, s21, 0xe000
	s_nop 0
	global_load_lds_dwordx4 v[176:177], off
	s_waitcnt vmcnt(8)
	s_waitcnt lgkmcnt(0)
	s_barrier
	s_setprio 1
	s_waitcnt lgkmcnt(0)
	v_mfma_f32_16x16x32_bf16 v[124:127], v[140:143], v[184:187], v[124:127]
	v_mfma_f32_16x16x32_bf16 v[120:123], v[148:151], v[184:187], v[120:123]
	v_mfma_f32_16x16x32_bf16 v[108:111], v[140:143], v[192:195], v[108:111]
	v_mfma_f32_16x16x32_bf16 v[104:107], v[148:151], v[192:195], v[104:107]
	v_mfma_f32_16x16x32_bf16 v[92:95], v[140:143], v[200:203], v[92:95]
	v_mfma_f32_16x16x32_bf16 v[88:91], v[148:151], v[200:203], v[88:91]
	v_mfma_f32_16x16x32_bf16 v[76:79], v[140:143], v[208:211], v[76:79]
	v_mfma_f32_16x16x32_bf16 v[72:75], v[148:151], v[208:211], v[72:75]
	v_mfma_f32_16x16x32_bf16 v[124:127], v[144:147], v[188:191], v[124:127]
	v_mfma_f32_16x16x32_bf16 v[120:123], v[152:155], v[188:191], v[120:123]
	v_mfma_f32_16x16x32_bf16 v[108:111], v[144:147], v[196:199], v[108:111]
	v_mfma_f32_16x16x32_bf16 v[104:107], v[152:155], v[196:199], v[104:107]
	v_mfma_f32_16x16x32_bf16 v[92:95], v[144:147], v[204:207], v[92:95]
	v_mfma_f32_16x16x32_bf16 v[88:91], v[152:155], v[204:207], v[88:91]
	v_mfma_f32_16x16x32_bf16 v[76:79], v[144:147], v[212:215], v[76:79]
	v_mfma_f32_16x16x32_bf16 v[72:75], v[152:155], v[212:215], v[72:75]
	v_mfma_f32_16x16x32_bf16 v[116:119], v[156:159], v[184:187], v[116:119]
	v_mfma_f32_16x16x32_bf16 v[112:115], v[164:167], v[184:187], v[112:115]
	v_mfma_f32_16x16x32_bf16 v[100:103], v[156:159], v[192:195], v[100:103]
	v_mfma_f32_16x16x32_bf16 v[96:99], v[164:167], v[192:195], v[96:99]
	v_mfma_f32_16x16x32_bf16 v[84:87], v[156:159], v[200:203], v[84:87]
	v_mfma_f32_16x16x32_bf16 v[80:83], v[164:167], v[200:203], v[80:83]
	v_mfma_f32_16x16x32_bf16 v[68:71], v[156:159], v[208:211], v[68:71]
	v_mfma_f32_16x16x32_bf16 v[64:67], v[164:167], v[208:211], v[64:67]
	v_mfma_f32_16x16x32_bf16 v[116:119], v[160:163], v[188:191], v[116:119]
	v_mfma_f32_16x16x32_bf16 v[112:115], v[180:183], v[188:191], v[112:115]
	v_mfma_f32_16x16x32_bf16 v[100:103], v[160:163], v[196:199], v[100:103]
	v_mfma_f32_16x16x32_bf16 v[96:99], v[180:183], v[196:199], v[96:99]
	v_mfma_f32_16x16x32_bf16 v[84:87], v[160:163], v[204:207], v[84:87]
	v_mfma_f32_16x16x32_bf16 v[80:83], v[180:183], v[204:207], v[80:83]
	v_mfma_f32_16x16x32_bf16 v[68:71], v[160:163], v[212:215], v[68:71]
	v_mfma_f32_16x16x32_bf16 v[64:67], v[180:183], v[212:215], v[64:67]
	s_setprio 0
	s_barrier
	s_add_i32 s24, s40, s20
	v_lshl_add_u64 v[176:177], s[26:27], 0, v[128:129]
	s_mov_b32 m0, s24
	ds_read_b128 v[184:187], v173 offset:16384
	ds_read_b128 v[188:191], v173 offset:17408
	ds_read_b128 v[192:195], v173 offset:18432
	ds_read_b128 v[196:199], v173 offset:19456
	ds_read_b128 v[200:203], v173 offset:20480
	ds_read_b128 v[204:207], v173 offset:21504
	ds_read_b128 v[208:211], v173 offset:22528
	ds_read_b128 v[212:215], v173 offset:23552
	global_load_lds_dwordx4 v[176:177], off
	s_add_i32 m0, s24, 0x2000
	s_add_u32 s24, s26, 0x160000
	v_lshl_add_u64 v[216:217], s[26:27], 0, v[130:131]
	s_addc_u32 s25, s27, 0
	s_add_i32 s50, s41, s20
	global_load_lds_dwordx4 v[216:217], off
	v_lshl_add_u64 v[218:219], s[24:25], 0, v[128:129]
	s_mov_b32 m0, s50
	v_lshl_add_u64 v[220:221], s[28:29], 0, v[130:131]
	global_load_lds_dwordx4 v[218:219], off
	v_lshl_add_u64 v[218:219], s[24:25], 0, v[130:131]
	s_add_i32 m0, s50, 0x2000
	s_nop 0
	global_load_lds_dwordx4 v[218:219], off
	v_lshl_add_u64 v[218:219], s[28:29], 0, v[128:129]
	s_mov_b32 m0, s21
	s_nop 0
	global_load_lds_dwordx4 v[218:219], off
	s_mov_b32 m0, s30
	s_nop 0
	global_load_lds_dwordx4 v[220:221], off
	s_waitcnt vmcnt(8)
	s_waitcnt lgkmcnt(0)
	s_barrier
	s_setprio 1
	s_waitcnt lgkmcnt(0)
	v_mfma_f32_16x16x32_bf16 v[60:63], v[140:143], v[184:187], v[60:63]
	v_mfma_f32_16x16x32_bf16 v[56:59], v[148:151], v[184:187], v[56:59]
	v_mfma_f32_16x16x32_bf16 v[44:47], v[140:143], v[192:195], v[44:47]
	v_mfma_f32_16x16x32_bf16 v[40:43], v[148:151], v[192:195], v[40:43]
	v_mfma_f32_16x16x32_bf16 v[28:31], v[140:143], v[200:203], v[28:31]
	v_mfma_f32_16x16x32_bf16 v[24:27], v[148:151], v[200:203], v[24:27]
	v_mfma_f32_16x16x32_bf16 v[12:15], v[140:143], v[208:211], v[12:15]
	v_mfma_f32_16x16x32_bf16 v[8:11], v[148:151], v[208:211], v[8:11]
	v_mfma_f32_16x16x32_bf16 v[60:63], v[144:147], v[188:191], v[60:63]
	v_mfma_f32_16x16x32_bf16 v[56:59], v[152:155], v[188:191], v[56:59]
	v_mfma_f32_16x16x32_bf16 v[44:47], v[144:147], v[196:199], v[44:47]
	v_mfma_f32_16x16x32_bf16 v[40:43], v[152:155], v[196:199], v[40:43]
	v_mfma_f32_16x16x32_bf16 v[28:31], v[144:147], v[204:207], v[28:31]
	v_mfma_f32_16x16x32_bf16 v[24:27], v[152:155], v[204:207], v[24:27]
	v_mfma_f32_16x16x32_bf16 v[12:15], v[144:147], v[212:215], v[12:15]
	v_mfma_f32_16x16x32_bf16 v[8:11], v[152:155], v[212:215], v[8:11]
	v_mfma_f32_16x16x32_bf16 v[52:55], v[156:159], v[184:187], v[52:55]
	v_mfma_f32_16x16x32_bf16 v[48:51], v[164:167], v[184:187], v[48:51]
	v_mfma_f32_16x16x32_bf16 v[36:39], v[156:159], v[192:195], v[36:39]
	v_mfma_f32_16x16x32_bf16 v[32:35], v[164:167], v[192:195], v[32:35]
	v_mfma_f32_16x16x32_bf16 v[20:23], v[156:159], v[200:203], v[20:23]
	v_mfma_f32_16x16x32_bf16 v[16:19], v[164:167], v[200:203], v[16:19]
	v_mfma_f32_16x16x32_bf16 v[4:7], v[156:159], v[208:211], v[4:7]
	v_mfma_f32_16x16x32_bf16 v[0:3], v[164:167], v[208:211], v[0:3]
	v_mfma_f32_16x16x32_bf16 v[52:55], v[160:163], v[188:191], v[52:55]
	v_mfma_f32_16x16x32_bf16 v[48:51], v[180:183], v[188:191], v[48:51]
	v_mfma_f32_16x16x32_bf16 v[36:39], v[160:163], v[196:199], v[36:39]
	v_mfma_f32_16x16x32_bf16 v[32:35], v[180:183], v[196:199], v[32:35]
	v_mfma_f32_16x16x32_bf16 v[20:23], v[160:163], v[204:207], v[20:23]
	v_mfma_f32_16x16x32_bf16 v[16:19], v[180:183], v[204:207], v[16:19]
	v_mfma_f32_16x16x32_bf16 v[4:7], v[160:163], v[212:215], v[4:7]
	v_mfma_f32_16x16x32_bf16 v[0:3], v[180:183], v[212:215], v[0:3]
	s_setprio 0
	s_barrier
	s_add_i32 s50, 0, 0x18000
	s_add_i32 s51, 0, 0x1c000
	v_add_u32_e32 v152, s50, v169
	v_add_u32_e32 v175, s51, v169
	ds_read_b128 v[140:143], v152
	ds_read_b128 v[144:147], v152 offset:1024
	ds_read_b128 v[148:151], v152 offset:2048
	ds_read_b128 v[152:155], v152 offset:3072
	ds_read_b128 v[156:159], v175
	ds_read_b128 v[160:163], v175 offset:1024
	ds_read_b128 v[164:167], v175 offset:2048
	ds_read_b128 v[180:183], v175 offset:3072
	s_add_u32 s24, s28, 0x160000
	s_addc_u32 s25, s29, 0
	s_mov_b32 m0, s31
	v_lshl_add_u64 v[222:223], s[24:25], 0, v[128:129]
	ds_read_b128 v[184:187], v173 offset:32768
	ds_read_b128 v[188:191], v173 offset:33792
	ds_read_b128 v[192:195], v173 offset:34816
	ds_read_b128 v[196:199], v173 offset:35840
	ds_read_b128 v[200:203], v173 offset:36864
	ds_read_b128 v[204:207], v173 offset:37888
	ds_read_b128 v[208:211], v173 offset:38912
	ds_read_b128 v[212:215], v173 offset:39936
	global_load_lds_dwordx4 v[222:223], off
	v_lshl_add_u64 v[222:223], s[24:25], 0, v[130:131]
	s_mov_b32 m0, s33
	s_nop 0
	global_load_lds_dwordx4 v[222:223], off
	s_waitcnt vmcnt(8)
	s_waitcnt lgkmcnt(0)
	s_barrier
	s_setprio 1
	s_waitcnt lgkmcnt(0)
	v_mfma_f32_16x16x32_bf16 v[124:127], v[140:143], v[184:187], v[124:127]
	v_mfma_f32_16x16x32_bf16 v[120:123], v[148:151], v[184:187], v[120:123]
	v_mfma_f32_16x16x32_bf16 v[108:111], v[140:143], v[192:195], v[108:111]
	v_mfma_f32_16x16x32_bf16 v[104:107], v[148:151], v[192:195], v[104:107]
	v_mfma_f32_16x16x32_bf16 v[92:95], v[140:143], v[200:203], v[92:95]
	v_mfma_f32_16x16x32_bf16 v[88:91], v[148:151], v[200:203], v[88:91]
	v_mfma_f32_16x16x32_bf16 v[76:79], v[140:143], v[208:211], v[76:79]
	v_mfma_f32_16x16x32_bf16 v[72:75], v[148:151], v[208:211], v[72:75]
	v_mfma_f32_16x16x32_bf16 v[124:127], v[144:147], v[188:191], v[124:127]
	v_mfma_f32_16x16x32_bf16 v[120:123], v[152:155], v[188:191], v[120:123]
	v_mfma_f32_16x16x32_bf16 v[108:111], v[144:147], v[196:199], v[108:111]
	v_mfma_f32_16x16x32_bf16 v[104:107], v[152:155], v[196:199], v[104:107]
	v_mfma_f32_16x16x32_bf16 v[92:95], v[144:147], v[204:207], v[92:95]
	v_mfma_f32_16x16x32_bf16 v[88:91], v[152:155], v[204:207], v[88:91]
	v_mfma_f32_16x16x32_bf16 v[76:79], v[144:147], v[212:215], v[76:79]
	v_mfma_f32_16x16x32_bf16 v[72:75], v[152:155], v[212:215], v[72:75]
	v_mfma_f32_16x16x32_bf16 v[116:119], v[156:159], v[184:187], v[116:119]
	v_mfma_f32_16x16x32_bf16 v[112:115], v[164:167], v[184:187], v[112:115]
	v_mfma_f32_16x16x32_bf16 v[100:103], v[156:159], v[192:195], v[100:103]
	v_mfma_f32_16x16x32_bf16 v[96:99], v[164:167], v[192:195], v[96:99]
	v_mfma_f32_16x16x32_bf16 v[84:87], v[156:159], v[200:203], v[84:87]
	v_mfma_f32_16x16x32_bf16 v[80:83], v[164:167], v[200:203], v[80:83]
	v_mfma_f32_16x16x32_bf16 v[68:71], v[156:159], v[208:211], v[68:71]
	v_mfma_f32_16x16x32_bf16 v[64:67], v[164:167], v[208:211], v[64:67]
	v_mfma_f32_16x16x32_bf16 v[116:119], v[160:163], v[188:191], v[116:119]
	v_mfma_f32_16x16x32_bf16 v[112:115], v[180:183], v[188:191], v[112:115]
	v_mfma_f32_16x16x32_bf16 v[100:103], v[160:163], v[196:199], v[100:103]
	v_mfma_f32_16x16x32_bf16 v[96:99], v[180:183], v[196:199], v[96:99]
	v_mfma_f32_16x16x32_bf16 v[84:87], v[160:163], v[204:207], v[84:87]
	v_mfma_f32_16x16x32_bf16 v[80:83], v[180:183], v[204:207], v[80:83]
	v_mfma_f32_16x16x32_bf16 v[68:71], v[160:163], v[212:215], v[68:71]
	v_mfma_f32_16x16x32_bf16 v[64:67], v[180:183], v[212:215], v[64:67]
	s_setprio 0
	s_barrier
	s_add_i32 s24, s50, s20
	v_lshl_add_u64 v[176:177], v[176:177], 0, s[10:11]
	s_mov_b32 m0, s24
	ds_read_b128 v[184:187], v173 offset:49152
	ds_read_b128 v[188:191], v173 offset:50176
	ds_read_b128 v[192:195], v173 offset:51200
	ds_read_b128 v[196:199], v173 offset:52224
	ds_read_b128 v[200:203], v173 offset:53248
	ds_read_b128 v[204:207], v173 offset:54272
	ds_read_b128 v[208:211], v173 offset:55296
	ds_read_b128 v[212:215], v173 offset:56320
	global_load_lds_dwordx4 v[176:177], off
	s_add_i32 m0, s24, 0x2000
	s_add_u32 s24, s26, 0x160080
	v_lshl_add_u64 v[176:177], v[216:217], 0, s[10:11]
	s_addc_u32 s25, s27, 0
	s_add_i32 s26, s51, s20
	global_load_lds_dwordx4 v[176:177], off
	v_lshl_add_u64 v[176:177], s[24:25], 0, v[128:129]
	s_mov_b32 m0, s26
	s_nop 0
	global_load_lds_dwordx4 v[176:177], off
	v_lshl_add_u64 v[176:177], s[24:25], 0, v[130:131]
	s_add_i32 m0, s26, 0x2000
	s_nop 0
	global_load_lds_dwordx4 v[176:177], off
	v_lshl_add_u64 v[176:177], v[218:219], 0, s[10:11]
	s_mov_b32 m0, s38
	s_nop 0
	global_load_lds_dwordx4 v[176:177], off
	v_lshl_add_u64 v[176:177], v[220:221], 0, s[10:11]
	s_mov_b32 m0, s39
	s_nop 0
	global_load_lds_dwordx4 v[176:177], off
	s_waitcnt vmcnt(8)
	s_waitcnt lgkmcnt(0)
	s_barrier
	s_setprio 1
	s_waitcnt lgkmcnt(0)
	v_mfma_f32_16x16x32_bf16 v[60:63], v[140:143], v[184:187], v[60:63]
	v_mfma_f32_16x16x32_bf16 v[56:59], v[148:151], v[184:187], v[56:59]
	v_mfma_f32_16x16x32_bf16 v[44:47], v[140:143], v[192:195], v[44:47]
	v_mfma_f32_16x16x32_bf16 v[40:43], v[148:151], v[192:195], v[40:43]
	v_mfma_f32_16x16x32_bf16 v[28:31], v[140:143], v[200:203], v[28:31]
	v_mfma_f32_16x16x32_bf16 v[24:27], v[148:151], v[200:203], v[24:27]
	v_mfma_f32_16x16x32_bf16 v[12:15], v[140:143], v[208:211], v[12:15]
	v_mfma_f32_16x16x32_bf16 v[8:11], v[148:151], v[208:211], v[8:11]
	v_mfma_f32_16x16x32_bf16 v[60:63], v[144:147], v[188:191], v[60:63]
	v_mfma_f32_16x16x32_bf16 v[56:59], v[152:155], v[188:191], v[56:59]
	v_mfma_f32_16x16x32_bf16 v[44:47], v[144:147], v[196:199], v[44:47]
	v_mfma_f32_16x16x32_bf16 v[40:43], v[152:155], v[196:199], v[40:43]
	v_mfma_f32_16x16x32_bf16 v[28:31], v[144:147], v[204:207], v[28:31]
	v_mfma_f32_16x16x32_bf16 v[24:27], v[152:155], v[204:207], v[24:27]
	v_mfma_f32_16x16x32_bf16 v[12:15], v[144:147], v[212:215], v[12:15]
	v_mfma_f32_16x16x32_bf16 v[8:11], v[152:155], v[212:215], v[8:11]
	v_mfma_f32_16x16x32_bf16 v[52:55], v[156:159], v[184:187], v[52:55]
	v_mfma_f32_16x16x32_bf16 v[48:51], v[164:167], v[184:187], v[48:51]
	v_mfma_f32_16x16x32_bf16 v[36:39], v[156:159], v[192:195], v[36:39]
	v_mfma_f32_16x16x32_bf16 v[32:35], v[164:167], v[192:195], v[32:35]
	v_mfma_f32_16x16x32_bf16 v[20:23], v[156:159], v[200:203], v[20:23]
	v_mfma_f32_16x16x32_bf16 v[16:19], v[164:167], v[200:203], v[16:19]
	v_mfma_f32_16x16x32_bf16 v[4:7], v[156:159], v[208:211], v[4:7]
	v_mfma_f32_16x16x32_bf16 v[0:3], v[164:167], v[208:211], v[0:3]
	v_mfma_f32_16x16x32_bf16 v[52:55], v[160:163], v[188:191], v[52:55]
	v_mfma_f32_16x16x32_bf16 v[48:51], v[180:183], v[188:191], v[48:51]
	v_mfma_f32_16x16x32_bf16 v[36:39], v[160:163], v[196:199], v[36:39]
	v_mfma_f32_16x16x32_bf16 v[32:35], v[180:183], v[196:199], v[32:35]
	v_mfma_f32_16x16x32_bf16 v[20:23], v[160:163], v[204:207], v[20:23]
	v_mfma_f32_16x16x32_bf16 v[16:19], v[180:183], v[204:207], v[16:19]
	v_mfma_f32_16x16x32_bf16 v[4:7], v[160:163], v[212:215], v[4:7]
	v_mfma_f32_16x16x32_bf16 v[0:3], v[180:183], v[212:215], v[0:3]
	s_setprio 0
	s_barrier
	s_add_i32 s49, s49, 2
	s_add_u32 s47, s47, 0x100
	s_addc_u32 s48, s48, 0
	s_cmpk_gt_u32 s49, 0x55
	s_mov_b64 s[24:25], s[22:23]
	s_cbranch_scc0 .LBB0_1040
	s_and_b64 vcc, exec, s[12:13]
	s_cbranch_vccz .LBB0_1043
	s_barrier
